# GEMM K-loop: first two counted waits after a tile epilogue leave the 16 epilogue stores in flight (vmcnt 24), so the next tile does not stall on store acks
# baseline (speedup 1.0000x reference)
.LBB0_26:
	v_and_b32_e32 v16, 48, v0
	v_lshlrev_b32_e32 v17, 6, v0
	s_movk_i32 s40, 0x3c0
	s_add_u32 s20, s60, 0x17a00000
	v_and_or_b32 v16, v17, s40, v16
	v_lshlrev_b32_e32 v17, 2, v0
	s_addc_u32 s21, s61, 0
	s_and_b32 s44, s38, 3
	s_lshl_b32 s38, s11, 6
	s_lshl_b32 s11, s11, 13
	v_and_b32_e32 v17, 32, v17
	s_add_i32 m0, s16, 0x18000
	v_lshl_add_u64 v[8:9], v[8:9], 0, s[34:35]
	v_bitop3_b32 v18, v16, s11, v17 bitop3:0xde
	s_lshl_b32 s11, s44, 12
	s_waitcnt vmcnt(2)
	s_barrier
	global_load_lds_dwordx4 v[8:9], off
	v_lshl_add_u64 v[6:7], v[6:7], 0, s[34:35]
	s_add_i32 m0, s16, 0x1a000
	s_add_i32 s49, s16, 0x8000
	s_add_i32 s56, s16, 0xa000
	global_load_lds_dwordx4 v[6:7], off
	v_lshl_add_u64 v[2:3], v[2:3], 0, s[34:35]
	s_mov_b32 m0, s49
	s_add_u32 s40, s8, 0x80080
	global_load_lds_dwordx4 v[2:3], off
	v_lshl_add_u64 v[2:3], v[4:5], 0, s[34:35]
	s_mov_b32 m0, s56
	s_addc_u32 s41, s9, 0
	global_load_lds_dwordx4 v[2:3], off
	s_add_i32 m0, s16, 0x1c000
	v_lshl_add_u64 v[2:3], s[40:41], 0, v[134:135]
	global_load_lds_dwordx4 v[2:3], off
	v_lshl_add_u64 v[2:3], s[40:41], 0, v[130:131]
	s_add_i32 m0, s16, 0x1e000
	v_and_b32_e32 v145, 63, v0
	global_load_lds_dwordx4 v[2:3], off
	v_lshlrev_b32_e32 v0, 15, v14
	v_and_b32_e32 v0, 0xffff0000, v0
	v_lshl_add_u32 v0, v13, 12, v0
	v_and_b32_e32 v2, 1, v14
	v_lshl_or_b32 v0, v2, 6, v0
	v_lshl_add_u32 v138, v15, 1, v0
	v_lshlrev_b32_e32 v0, 15, v10
	v_and_b32_e32 v0, 0xffff0000, v0
	s_waitcnt vmcnt(6)
	v_lshl_add_u32 v0, v11, 12, v0
	v_and_b32_e32 v2, 1, v10
	v_bitop3_b32 v144, v16, s11, v17 bitop3:0xde
	s_cmpk_lt_u32 s10, 0x100
	v_lshl_or_b32 v0, v2, 6, v0
	v_readlane_b32 s10, v254, 36
	s_cselect_b64 s[42:43], -1, 0
	s_lshl_b32 s57, s44, 6
	v_mov_b32_e32 v139, v1
	v_lshl_add_u32 v140, v12, 1, v0
	v_mov_b32_e32 v141, v1
	s_mov_b32 s58, 0
	v_add_u32_e32 v146, 0, v18
	v_readlane_b32 s59, v254, 28
	s_mov_b32 s62, s10
	s_barrier
	v_readlane_b32 s11, v254, 37
	s_mov_b32 s98, 0
	s_branch .LBB0_29

.LBB0_36:
	s_add_u32 s8, s6, 0xfff80080
	s_addc_u32 s9, s7, -1
	s_add_i32 s68, 0, 0x10000
	s_cmp_eq_u32 s67, 28
	s_cselect_b32 s11, s47, s9
	s_cselect_b32 s10, s63, s8
	v_add_u32_e32 v0, s68, v144
	s_cselect_b32 s9, s45, s66
	s_cselect_b32 s8, s64, s65
	s_add_i32 s70, 0, 0x14000
	ds_read_b128 v[148:151], v0
	ds_read_b128 v[152:155], v0 offset:1024
	ds_read_b128 v[156:159], v0 offset:2048
	ds_read_b128 v[166:169], v0 offset:3072
	v_add_u32_e32 v0, s70, v144
	ds_read_b128 v[170:173], v0
	ds_read_b128 v[174:177], v0 offset:1024
	ds_read_b128 v[178:181], v0 offset:2048
	ds_read_b128 v[182:185], v0 offset:3072
	v_lshl_add_u64 v[142:143], s[6:7], 0, v[138:139]
	s_add_i32 m0, s16, 0xc000
	ds_read_b128 v[186:189], v146
	ds_read_b128 v[190:193], v146 offset:1024
	ds_read_b128 v[194:197], v146 offset:2048
	ds_read_b128 v[198:201], v146 offset:3072
	ds_read_b128 v[202:205], v146 offset:4096
	ds_read_b128 v[206:209], v146 offset:5120
	ds_read_b128 v[210:213], v146 offset:6144
	ds_read_b128 v[214:217], v146 offset:7168
	global_load_lds_dwordx4 v[142:143], off
	v_lshl_add_u64 v[142:143], s[6:7], 0, v[140:141]
	s_add_i32 m0, s16, 0xe000
	s_nop 0
	global_load_lds_dwordx4 v[142:143], off
	s_cmp_lg_u32 s98, 0
	s_cbranch_scc1 .Lgw1a_r
	s_waitcnt vmcnt(8)
.Lgw1a_d:
	s_waitcnt lgkmcnt(0)
	s_barrier
	s_setprio 1
	s_waitcnt lgkmcnt(0)
	v_mfma_f32_16x16x32_bf16 v[126:129], v[148:151], v[186:189], v[126:129]
	v_mfma_f32_16x16x32_bf16 v[122:125], v[156:159], v[186:189], v[122:125]
	v_mfma_f32_16x16x32_bf16 v[110:113], v[148:151], v[194:197], v[110:113]
	v_mfma_f32_16x16x32_bf16 v[106:109], v[156:159], v[194:197], v[106:109]
	v_mfma_f32_16x16x32_bf16 v[94:97], v[148:151], v[202:205], v[94:97]
	v_mfma_f32_16x16x32_bf16 v[90:93], v[156:159], v[202:205], v[90:93]
	v_mfma_f32_16x16x32_bf16 v[78:81], v[148:151], v[210:213], v[78:81]
	v_mfma_f32_16x16x32_bf16 v[74:77], v[156:159], v[210:213], v[74:77]
	v_mfma_f32_16x16x32_bf16 v[126:129], v[152:155], v[190:193], v[126:129]
	v_mfma_f32_16x16x32_bf16 v[122:125], v[166:169], v[190:193], v[122:125]
	v_mfma_f32_16x16x32_bf16 v[110:113], v[152:155], v[198:201], v[110:113]
	v_mfma_f32_16x16x32_bf16 v[106:109], v[166:169], v[198:201], v[106:109]
	v_mfma_f32_16x16x32_bf16 v[94:97], v[152:155], v[206:209], v[94:97]
	v_mfma_f32_16x16x32_bf16 v[90:93], v[166:169], v[206:209], v[90:93]
	v_mfma_f32_16x16x32_bf16 v[78:81], v[152:155], v[214:217], v[78:81]
	v_mfma_f32_16x16x32_bf16 v[74:77], v[166:169], v[214:217], v[74:77]
	s_setprio 0
	s_setprio 1
	v_mfma_f32_16x16x32_bf16 v[118:121], v[170:173], v[186:189], v[118:121]
	v_mfma_f32_16x16x32_bf16 v[114:117], v[178:181], v[186:189], v[114:117]
	v_mfma_f32_16x16x32_bf16 v[102:105], v[170:173], v[194:197], v[102:105]
	v_mfma_f32_16x16x32_bf16 v[98:101], v[178:181], v[194:197], v[98:101]
	v_mfma_f32_16x16x32_bf16 v[86:89], v[170:173], v[202:205], v[86:89]
	v_mfma_f32_16x16x32_bf16 v[82:85], v[178:181], v[202:205], v[82:85]
	v_mfma_f32_16x16x32_bf16 v[70:73], v[170:173], v[210:213], v[70:73]
	v_mfma_f32_16x16x32_bf16 v[66:69], v[178:181], v[210:213], v[66:69]
	v_mfma_f32_16x16x32_bf16 v[118:121], v[174:177], v[190:193], v[118:121]
	v_mfma_f32_16x16x32_bf16 v[114:117], v[182:185], v[190:193], v[114:117]
	v_mfma_f32_16x16x32_bf16 v[102:105], v[174:177], v[198:201], v[102:105]
	v_mfma_f32_16x16x32_bf16 v[98:101], v[182:185], v[198:201], v[98:101]
	v_mfma_f32_16x16x32_bf16 v[86:89], v[174:177], v[206:209], v[86:89]
	v_mfma_f32_16x16x32_bf16 v[82:85], v[182:185], v[206:209], v[82:85]
	v_mfma_f32_16x16x32_bf16 v[70:73], v[174:177], v[214:217], v[70:73]
	v_mfma_f32_16x16x32_bf16 v[66:69], v[182:185], v[214:217], v[66:69]
	s_setprio 0
	s_barrier
	s_add_i32 s68, s68, s15
	v_lshl_add_u64 v[142:143], s[8:9], 0, v[134:135]
	s_mov_b32 m0, s68
	ds_read_b128 v[186:189], v146 offset:16384
	ds_read_b128 v[190:193], v146 offset:17408
	ds_read_b128 v[194:197], v146 offset:18432
	ds_read_b128 v[198:201], v146 offset:19456
	ds_read_b128 v[202:205], v146 offset:20480
	ds_read_b128 v[206:209], v146 offset:21504
	ds_read_b128 v[210:213], v146 offset:22528
	ds_read_b128 v[214:217], v146 offset:23552
	global_load_lds_dwordx4 v[142:143], off
	s_add_i32 m0, s68, 0x2000
	s_add_u32 s72, s8, 0x80000
	v_lshl_add_u64 v[160:161], s[8:9], 0, v[130:131]
	s_addc_u32 s73, s9, 0
	s_add_i32 s68, s70, s15
	global_load_lds_dwordx4 v[160:161], off
	v_lshl_add_u64 v[218:219], s[72:73], 0, v[134:135]
	s_mov_b32 m0, s68
	v_lshl_add_u64 v[220:221], s[10:11], 0, v[132:133]
	global_load_lds_dwordx4 v[218:219], off
	v_lshl_add_u64 v[218:219], s[72:73], 0, v[130:131]
	s_add_i32 m0, s68, 0x2000
	s_nop 0
	global_load_lds_dwordx4 v[218:219], off
	v_lshl_add_u64 v[218:219], s[10:11], 0, v[136:137]
	s_mov_b32 m0, s16
	s_nop 0
	global_load_lds_dwordx4 v[218:219], off
	s_mov_b32 m0, s17
	s_nop 0
	global_load_lds_dwordx4 v[220:221], off
	s_cmp_lg_u32 s98, 0
	s_cbranch_scc1 .Lgw1b_r
	s_waitcnt vmcnt(8)
.Lgw1b_d:
	s_waitcnt lgkmcnt(0)
	s_barrier
	s_setprio 1
	s_waitcnt lgkmcnt(0)
	v_mfma_f32_16x16x32_bf16 v[62:65], v[148:151], v[186:189], v[62:65]
	v_mfma_f32_16x16x32_bf16 v[58:61], v[156:159], v[186:189], v[58:61]
	v_mfma_f32_16x16x32_bf16 v[46:49], v[148:151], v[194:197], v[46:49]
	v_mfma_f32_16x16x32_bf16 v[42:45], v[156:159], v[194:197], v[42:45]
	v_mfma_f32_16x16x32_bf16 v[30:33], v[148:151], v[202:205], v[30:33]
	v_mfma_f32_16x16x32_bf16 v[26:29], v[156:159], v[202:205], v[26:29]
	v_mfma_f32_16x16x32_bf16 v[14:17], v[148:151], v[210:213], v[14:17]
	v_mfma_f32_16x16x32_bf16 v[10:13], v[156:159], v[210:213], v[10:13]
	v_mfma_f32_16x16x32_bf16 v[62:65], v[152:155], v[190:193], v[62:65]
	v_mfma_f32_16x16x32_bf16 v[58:61], v[166:169], v[190:193], v[58:61]
	v_mfma_f32_16x16x32_bf16 v[46:49], v[152:155], v[198:201], v[46:49]
	v_mfma_f32_16x16x32_bf16 v[42:45], v[166:169], v[198:201], v[42:45]
	v_mfma_f32_16x16x32_bf16 v[30:33], v[152:155], v[206:209], v[30:33]
	v_mfma_f32_16x16x32_bf16 v[26:29], v[166:169], v[206:209], v[26:29]
	v_mfma_f32_16x16x32_bf16 v[14:17], v[152:155], v[214:217], v[14:17]
	v_mfma_f32_16x16x32_bf16 v[10:13], v[166:169], v[214:217], v[10:13]
	s_setprio 0
	s_setprio 1
	v_mfma_f32_16x16x32_bf16 v[54:57], v[170:173], v[186:189], v[54:57]
	v_mfma_f32_16x16x32_bf16 v[50:53], v[178:181], v[186:189], v[50:53]
	v_mfma_f32_16x16x32_bf16 v[38:41], v[170:173], v[194:197], v[38:41]
	v_mfma_f32_16x16x32_bf16 v[34:37], v[178:181], v[194:197], v[34:37]
	v_mfma_f32_16x16x32_bf16 v[22:25], v[170:173], v[202:205], v[22:25]
	v_mfma_f32_16x16x32_bf16 v[18:21], v[178:181], v[202:205], v[18:21]
	v_mfma_f32_16x16x32_bf16 v[6:9], v[170:173], v[210:213], v[6:9]
	v_mfma_f32_16x16x32_bf16 v[2:5], v[178:181], v[210:213], v[2:5]
	v_mfma_f32_16x16x32_bf16 v[54:57], v[174:177], v[190:193], v[54:57]
	v_mfma_f32_16x16x32_bf16 v[50:53], v[182:185], v[190:193], v[50:53]
	v_mfma_f32_16x16x32_bf16 v[38:41], v[174:177], v[198:201], v[38:41]
	v_mfma_f32_16x16x32_bf16 v[34:37], v[182:185], v[198:201], v[34:37]
	v_mfma_f32_16x16x32_bf16 v[22:25], v[174:177], v[206:209], v[22:25]
	v_mfma_f32_16x16x32_bf16 v[18:21], v[182:185], v[206:209], v[18:21]
	v_mfma_f32_16x16x32_bf16 v[6:9], v[174:177], v[214:217], v[6:9]
	v_mfma_f32_16x16x32_bf16 v[2:5], v[182:185], v[214:217], v[2:5]
	s_setprio 0
	s_barrier
	s_add_i32 s68, 0, 0x18000
	v_add_u32_e32 v0, s68, v144
	s_add_i32 s70, 0, 0x1c000
	ds_read_b128 v[148:151], v0
	ds_read_b128 v[152:155], v0 offset:1024
	ds_read_b128 v[156:159], v0 offset:2048
	ds_read_b128 v[166:169], v0 offset:3072
	v_add_u32_e32 v0, s70, v144
	ds_read_b128 v[170:173], v0
	ds_read_b128 v[174:177], v0 offset:1024
	ds_read_b128 v[178:181], v0 offset:2048
	ds_read_b128 v[182:185], v0 offset:3072
	s_add_u32 s10, s10, 0x80000
	s_addc_u32 s11, s11, 0
	s_mov_b32 m0, s18
	v_lshl_add_u64 v[222:223], s[10:11], 0, v[136:137]
	ds_read_b128 v[186:189], v146 offset:32768
	ds_read_b128 v[190:193], v146 offset:33792
	ds_read_b128 v[194:197], v146 offset:34816
	ds_read_b128 v[198:201], v146 offset:35840
	ds_read_b128 v[202:205], v146 offset:36864
	ds_read_b128 v[206:209], v146 offset:37888
	ds_read_b128 v[210:213], v146 offset:38912
	ds_read_b128 v[214:217], v146 offset:39936
	global_load_lds_dwordx4 v[222:223], off
	v_lshl_add_u64 v[222:223], s[10:11], 0, v[132:133]
	s_mov_b32 m0, s19
	s_nop 0
	global_load_lds_dwordx4 v[222:223], off
	s_waitcnt vmcnt(8)
	s_waitcnt lgkmcnt(0)
	s_barrier
	s_setprio 1
	s_waitcnt lgkmcnt(0)
	v_mfma_f32_16x16x32_bf16 v[126:129], v[148:151], v[186:189], v[126:129]
	v_mfma_f32_16x16x32_bf16 v[122:125], v[156:159], v[186:189], v[122:125]
	v_mfma_f32_16x16x32_bf16 v[110:113], v[148:151], v[194:197], v[110:113]
	v_mfma_f32_16x16x32_bf16 v[106:109], v[156:159], v[194:197], v[106:109]
	v_mfma_f32_16x16x32_bf16 v[94:97], v[148:151], v[202:205], v[94:97]
	v_mfma_f32_16x16x32_bf16 v[90:93], v[156:159], v[202:205], v[90:93]
	v_mfma_f32_16x16x32_bf16 v[78:81], v[148:151], v[210:213], v[78:81]
	v_mfma_f32_16x16x32_bf16 v[74:77], v[156:159], v[210:213], v[74:77]
	v_mfma_f32_16x16x32_bf16 v[126:129], v[152:155], v[190:193], v[126:129]
	v_mfma_f32_16x16x32_bf16 v[122:125], v[166:169], v[190:193], v[122:125]
	v_mfma_f32_16x16x32_bf16 v[110:113], v[152:155], v[198:201], v[110:113]
	v_mfma_f32_16x16x32_bf16 v[106:109], v[166:169], v[198:201], v[106:109]
	v_mfma_f32_16x16x32_bf16 v[94:97], v[152:155], v[206:209], v[94:97]
	v_mfma_f32_16x16x32_bf16 v[90:93], v[166:169], v[206:209], v[90:93]
	v_mfma_f32_16x16x32_bf16 v[78:81], v[152:155], v[214:217], v[78:81]
	v_mfma_f32_16x16x32_bf16 v[74:77], v[166:169], v[214:217], v[74:77]
	s_setprio 0
	s_setprio 1
	v_mfma_f32_16x16x32_bf16 v[118:121], v[170:173], v[186:189], v[118:121]
	v_mfma_f32_16x16x32_bf16 v[114:117], v[178:181], v[186:189], v[114:117]
	v_mfma_f32_16x16x32_bf16 v[102:105], v[170:173], v[194:197], v[102:105]
	v_mfma_f32_16x16x32_bf16 v[98:101], v[178:181], v[194:197], v[98:101]
	v_mfma_f32_16x16x32_bf16 v[86:89], v[170:173], v[202:205], v[86:89]
	v_mfma_f32_16x16x32_bf16 v[82:85], v[178:181], v[202:205], v[82:85]
	v_mfma_f32_16x16x32_bf16 v[70:73], v[170:173], v[210:213], v[70:73]
	v_mfma_f32_16x16x32_bf16 v[66:69], v[178:181], v[210:213], v[66:69]
	v_mfma_f32_16x16x32_bf16 v[118:121], v[174:177], v[190:193], v[118:121]
	v_mfma_f32_16x16x32_bf16 v[114:117], v[182:185], v[190:193], v[114:117]
	v_mfma_f32_16x16x32_bf16 v[102:105], v[174:177], v[198:201], v[102:105]
	v_mfma_f32_16x16x32_bf16 v[98:101], v[182:185], v[198:201], v[98:101]
	v_mfma_f32_16x16x32_bf16 v[86:89], v[174:177], v[206:209], v[86:89]
	v_mfma_f32_16x16x32_bf16 v[82:85], v[182:185], v[206:209], v[82:85]
	v_mfma_f32_16x16x32_bf16 v[70:73], v[174:177], v[214:217], v[70:73]
	v_mfma_f32_16x16x32_bf16 v[66:69], v[182:185], v[214:217], v[66:69]
	s_setprio 0
	s_barrier
	s_add_i32 s10, s68, s15
	v_lshl_add_u64 v[142:143], v[142:143], 0, s[34:35]
	s_mov_b32 m0, s10
	ds_read_b128 v[186:189], v146 offset:49152
	ds_read_b128 v[190:193], v146 offset:50176
	ds_read_b128 v[194:197], v146 offset:51200
	ds_read_b128 v[198:201], v146 offset:52224
	ds_read_b128 v[202:205], v146 offset:53248
	ds_read_b128 v[206:209], v146 offset:54272
	ds_read_b128 v[210:213], v146 offset:55296
	ds_read_b128 v[214:217], v146 offset:56320
	global_load_lds_dwordx4 v[142:143], off
	s_add_i32 m0, s10, 0x2000
	s_add_u32 s8, s8, 0x80080
	v_lshl_add_u64 v[142:143], v[160:161], 0, s[34:35]
	s_addc_u32 s9, s9, 0
	s_add_i32 s10, s70, s15
	global_load_lds_dwordx4 v[142:143], off
	v_lshl_add_u64 v[142:143], s[8:9], 0, v[134:135]
	s_mov_b32 m0, s10
	s_nop 0
	global_load_lds_dwordx4 v[142:143], off
	v_lshl_add_u64 v[142:143], s[8:9], 0, v[130:131]
	s_add_i32 m0, s10, 0x2000
	s_nop 0
	global_load_lds_dwordx4 v[142:143], off
	v_lshl_add_u64 v[142:143], v[218:219], 0, s[34:35]
	s_mov_b32 m0, s49
	s_nop 0
	global_load_lds_dwordx4 v[142:143], off
	v_lshl_add_u64 v[142:143], v[220:221], 0, s[34:35]
	s_mov_b32 m0, s56
	s_nop 0
	global_load_lds_dwordx4 v[142:143], off
	s_waitcnt vmcnt(8)
	s_waitcnt lgkmcnt(0)
	s_barrier
	s_setprio 1
	s_waitcnt lgkmcnt(0)
	v_mfma_f32_16x16x32_bf16 v[62:65], v[148:151], v[186:189], v[62:65]
	v_mfma_f32_16x16x32_bf16 v[58:61], v[156:159], v[186:189], v[58:61]
	v_mfma_f32_16x16x32_bf16 v[46:49], v[148:151], v[194:197], v[46:49]
	v_mfma_f32_16x16x32_bf16 v[42:45], v[156:159], v[194:197], v[42:45]
	v_mfma_f32_16x16x32_bf16 v[30:33], v[148:151], v[202:205], v[30:33]
	v_mfma_f32_16x16x32_bf16 v[26:29], v[156:159], v[202:205], v[26:29]
	v_mfma_f32_16x16x32_bf16 v[14:17], v[148:151], v[210:213], v[14:17]
	v_mfma_f32_16x16x32_bf16 v[10:13], v[156:159], v[210:213], v[10:13]
	v_mfma_f32_16x16x32_bf16 v[62:65], v[152:155], v[190:193], v[62:65]
	v_mfma_f32_16x16x32_bf16 v[58:61], v[166:169], v[190:193], v[58:61]
	v_mfma_f32_16x16x32_bf16 v[46:49], v[152:155], v[198:201], v[46:49]
	v_mfma_f32_16x16x32_bf16 v[42:45], v[166:169], v[198:201], v[42:45]
	v_mfma_f32_16x16x32_bf16 v[30:33], v[152:155], v[206:209], v[30:33]
	v_mfma_f32_16x16x32_bf16 v[26:29], v[166:169], v[206:209], v[26:29]
	v_mfma_f32_16x16x32_bf16 v[14:17], v[152:155], v[214:217], v[14:17]
	v_mfma_f32_16x16x32_bf16 v[10:13], v[166:169], v[214:217], v[10:13]
	s_setprio 0
	s_setprio 1
	v_mfma_f32_16x16x32_bf16 v[54:57], v[170:173], v[186:189], v[54:57]
	v_mfma_f32_16x16x32_bf16 v[50:53], v[178:181], v[186:189], v[50:53]
	v_mfma_f32_16x16x32_bf16 v[38:41], v[170:173], v[194:197], v[38:41]
	v_mfma_f32_16x16x32_bf16 v[34:37], v[178:181], v[194:197], v[34:37]
	v_mfma_f32_16x16x32_bf16 v[22:25], v[170:173], v[202:205], v[22:25]
	v_mfma_f32_16x16x32_bf16 v[18:21], v[178:181], v[202:205], v[18:21]
	v_mfma_f32_16x16x32_bf16 v[6:9], v[170:173], v[210:213], v[6:9]
	v_mfma_f32_16x16x32_bf16 v[2:5], v[178:181], v[210:213], v[2:5]
	v_mfma_f32_16x16x32_bf16 v[54:57], v[174:177], v[190:193], v[54:57]
	v_mfma_f32_16x16x32_bf16 v[50:53], v[182:185], v[190:193], v[50:53]
	v_mfma_f32_16x16x32_bf16 v[38:41], v[174:177], v[198:201], v[38:41]
	v_mfma_f32_16x16x32_bf16 v[34:37], v[182:185], v[198:201], v[34:37]
	v_mfma_f32_16x16x32_bf16 v[22:25], v[174:177], v[206:209], v[22:25]
	v_mfma_f32_16x16x32_bf16 v[18:21], v[182:185], v[206:209], v[18:21]
	v_mfma_f32_16x16x32_bf16 v[6:9], v[174:177], v[214:217], v[6:9]
	v_mfma_f32_16x16x32_bf16 v[2:5], v[182:185], v[214:217], v[2:5]
	s_setprio 0
	s_barrier
	s_add_i32 s67, s67, 2
	s_add_u32 s6, s6, 0x100
	s_addc_u32 s7, s7, 0
	s_add_u32 s65, s65, 0x100
	s_addc_u32 s66, s66, 0
	s_cmp_gt_u32 s67, 29
	s_cbranch_scc0 .LBB0_36
	s_and_b64 vcc, exec, s[42:43]
	s_mov_b64 s[64:65], 0x29100000
	s_mov_b64 s[66:67], 0x2000
	s_cbranch_vccz .LBB0_39
	s_barrier
.LBB0_39:
	s_mov_b32 s98, 1
	s_lshl_b32 s6, s62, 8
	s_ashr_i32 s7, s6, 31
	s_lshl_b64 s[6:7], s[6:7], 14
	s_add_u32 s8, s20, s6
	s_addc_u32 s9, s21, s7
	s_lshl_b32 s6, s59, 8
	v_max_f32_e32 v122, 0, v122
	v_mov_b32_e32 v0, v145
	s_ashr_i32 s7, s6, 31
	v_mul_f32_e32 v147, v122, v122
	v_max_f32_e32 v123, 0, v123
	v_max_f32_e32 v124, 0, v124
	s_lshl_b64 s[6:7], s[6:7], 1
	v_and_or_b32 v142, v0, 15, s38
	v_max_f32_e32 v122, 0, v127
	v_mul_f32_e32 v127, v123, v123
	v_max_f32_e32 v123, v128, v128
	v_mul_f32_e32 v128, v124, v124
	s_add_u32 s6, s8, s6
	v_lshlrev_b32_e32 v142, 14, v142
	v_and_b32_e32 v0, -16, v0
	v_max_f32_e32 v126, 0, v126
	v_mul_f32_e32 v122, v122, v122
	v_max_f32_e32 v123, 0, v123
	v_max_f32_e32 v124, 0, v129
	v_max_f32_e32 v125, 0, v125
	s_addc_u32 s7, s9, s7
	v_add3_u32 v0, v0, s57, v142
	v_mul_f32_e32 v126, v126, v126
	v_mul_f32_e32 v123, v123, v123
	v_mul_f32_e32 v124, v124, v124
	v_mul_f32_e32 v125, v125, v125
	v_cvt_pk_bf16_f32 v122, v126, v122
	v_max_f32_e32 v114, 0, v114
	v_max_f32_e32 v115, 0, v115
	v_max_f32_e32 v116, 0, v116
	v_cvt_pk_bf16_f32 v123, v123, v124
	v_cvt_pk_bf16_f32 v124, v147, v127
	v_cvt_pk_bf16_f32 v125, v128, v125
	global_store_dwordx4 v0, v[122:125], s[6:7]
	s_nop 1
	v_mul_f32_e32 v122, v114, v114
	v_max_f32_e32 v114, v119, v119
	v_mul_f32_e32 v119, v115, v115
	v_max_f32_e32 v115, v120, v120
	v_mul_f32_e32 v120, v116, v116
	v_max_f32_e32 v114, 0, v114
	v_max_f32_e32 v115, 0, v115
	v_max_f32_e32 v116, 0, v121
	v_max_f32_e32 v117, 0, v117
	v_max_f32_e32 v118, 0, v118
	v_mul_f32_e32 v114, v114, v114
	v_mul_f32_e32 v115, v115, v115
	v_mul_f32_e32 v116, v116, v116
	v_mul_f32_e32 v117, v117, v117
	v_max_f32_e32 v106, 0, v106
	v_lshl_add_u64 v[142:143], s[6:7], 0, v[0:1]
	v_mul_f32_e32 v118, v118, v118
	v_cvt_pk_bf16_f32 v114, v118, v114
	v_cvt_pk_bf16_f32 v115, v115, v116
	v_cvt_pk_bf16_f32 v116, v122, v119
	v_cvt_pk_bf16_f32 v117, v120, v117
	global_store_dwordx4 v0, v[114:117], s[6:7] offset:256
	s_nop 1
	v_max_f32_e32 v0, v110, v110
	v_mul_f32_e32 v110, v106, v106
	v_max_f32_e32 v107, 0, v107
	v_max_f32_e32 v108, 0, v108
	v_max_f32_e32 v0, 0, v0
	v_max_f32_e32 v106, 0, v111
	v_mul_f32_e32 v111, v107, v107
	v_max_f32_e32 v107, v112, v112
	v_mul_f32_e32 v112, v108, v108
	v_mul_f32_e32 v0, v0, v0
	v_mul_f32_e32 v106, v106, v106
	v_max_f32_e32 v107, 0, v107
	v_max_f32_e32 v108, 0, v113
	v_max_f32_e32 v98, 0, v98
	v_mul_f32_e32 v107, v107, v107
	v_mul_f32_e32 v108, v108, v108
	v_cvt_pk_bf16_f32 v106, v0, v106
	s_mov_b32 s6, 0x40000
	v_max_f32_e32 v0, v102, v102
	v_mul_f32_e32 v102, v98, v98
	v_max_f32_e32 v109, 0, v109
	v_cvt_pk_bf16_f32 v107, v107, v108
	v_cvt_pk_bf16_f32 v108, v110, v111
	v_add_co_u32_e32 v110, vcc, s6, v142
	v_max_f32_e32 v0, 0, v0
	v_max_f32_e32 v98, 0, v103
	v_mul_f32_e32 v109, v109, v109
	v_addc_co_u32_e32 v111, vcc, 0, v143, vcc
	v_mul_f32_e32 v0, v0, v0
	v_max_f32_e32 v99, 0, v99
	v_mul_f32_e32 v98, v98, v98
	v_max_f32_e32 v100, 0, v100
	v_max_f32_e32 v90, 0, v90
	v_cvt_pk_bf16_f32 v109, v112, v109
	global_store_dwordx4 v[110:111], v[106:109], off
	s_nop 1
	v_mul_f32_e32 v103, v99, v99
	v_max_f32_e32 v99, v104, v104
	v_mul_f32_e32 v104, v100, v100
	v_cvt_pk_bf16_f32 v98, v0, v98
	v_max_f32_e32 v0, v94, v94
	v_mul_f32_e32 v94, v90, v90
	v_max_f32_e32 v91, 0, v91
	v_max_f32_e32 v92, 0, v92
	v_max_f32_e32 v99, 0, v99
	v_max_f32_e32 v100, 0, v105
	v_max_f32_e32 v101, 0, v101
	v_max_f32_e32 v0, 0, v0
	v_max_f32_e32 v90, 0, v95
	v_mul_f32_e32 v95, v91, v91
	v_max_f32_e32 v91, v96, v96
	v_mul_f32_e32 v96, v92, v92
	v_mul_f32_e32 v99, v99, v99
	v_mul_f32_e32 v100, v100, v100
	v_mul_f32_e32 v101, v101, v101
	v_mul_f32_e32 v0, v0, v0
	v_mul_f32_e32 v90, v90, v90
	v_max_f32_e32 v91, 0, v91
	v_max_f32_e32 v92, 0, v97
	v_max_f32_e32 v82, 0, v82
	v_cvt_pk_bf16_f32 v99, v99, v100
	v_cvt_pk_bf16_f32 v100, v102, v103
	v_cvt_pk_bf16_f32 v101, v104, v101
	global_store_dwordx4 v[110:111], v[98:101], off offset:256
	s_nop 1
	v_mul_f32_e32 v91, v91, v91
	v_mul_f32_e32 v92, v92, v92
	v_cvt_pk_bf16_f32 v90, v0, v90
	s_mov_b32 s6, 0x80000
	v_max_f32_e32 v0, v86, v86
	v_mul_f32_e32 v86, v82, v82
	v_max_f32_e32 v93, 0, v93
	v_cvt_pk_bf16_f32 v91, v91, v92
	v_cvt_pk_bf16_f32 v92, v94, v95
	v_add_co_u32_e32 v94, vcc, s6, v142
	v_max_f32_e32 v0, 0, v0
	v_max_f32_e32 v82, 0, v87
	v_mul_f32_e32 v93, v93, v93
	v_addc_co_u32_e32 v95, vcc, 0, v143, vcc
	v_mul_f32_e32 v0, v0, v0
	v_max_f32_e32 v83, 0, v83
	v_mul_f32_e32 v82, v82, v82
	v_max_f32_e32 v84, 0, v84
	v_max_f32_e32 v74, 0, v74
	v_cvt_pk_bf16_f32 v93, v96, v93
	global_store_dwordx4 v[94:95], v[90:93], off
	s_nop 1
	v_mul_f32_e32 v87, v83, v83
	v_max_f32_e32 v83, v88, v88
	v_mul_f32_e32 v88, v84, v84
	v_cvt_pk_bf16_f32 v82, v0, v82
	v_max_f32_e32 v0, v78, v78
	v_mul_f32_e32 v78, v74, v74
	v_max_f32_e32 v75, 0, v75
	v_max_f32_e32 v76, 0, v76
	v_max_f32_e32 v83, 0, v83
	v_max_f32_e32 v84, 0, v89
	v_max_f32_e32 v85, 0, v85
	v_max_f32_e32 v0, 0, v0
	v_max_f32_e32 v74, 0, v79
	v_mul_f32_e32 v79, v75, v75
	v_max_f32_e32 v75, v80, v80
	v_mul_f32_e32 v80, v76, v76
	v_mul_f32_e32 v83, v83, v83
	v_mul_f32_e32 v84, v84, v84
	v_mul_f32_e32 v85, v85, v85
	v_mul_f32_e32 v0, v0, v0
	v_mul_f32_e32 v74, v74, v74
	v_max_f32_e32 v75, 0, v75
	v_max_f32_e32 v76, 0, v81
	v_max_f32_e32 v66, 0, v66
	v_cvt_pk_bf16_f32 v83, v83, v84
	v_cvt_pk_bf16_f32 v84, v86, v87
	v_cvt_pk_bf16_f32 v85, v88, v85
	global_store_dwordx4 v[94:95], v[82:85], off offset:256
	s_nop 1
	v_mul_f32_e32 v75, v75, v75
	v_mul_f32_e32 v76, v76, v76
	v_cvt_pk_bf16_f32 v74, v0, v74
	s_mov_b32 s6, 0xc0000
	v_max_f32_e32 v0, v70, v70
	v_mul_f32_e32 v70, v66, v66
	v_max_f32_e32 v77, 0, v77
	v_cvt_pk_bf16_f32 v75, v75, v76
	v_cvt_pk_bf16_f32 v76, v78, v79
	v_add_co_u32_e32 v78, vcc, s6, v142
	v_max_f32_e32 v0, 0, v0
	v_max_f32_e32 v66, 0, v71
	v_mul_f32_e32 v77, v77, v77
	v_addc_co_u32_e32 v79, vcc, 0, v143, vcc
	v_mul_f32_e32 v0, v0, v0
	v_max_f32_e32 v67, 0, v67
	v_mul_f32_e32 v66, v66, v66
	v_max_f32_e32 v68, 0, v68
	v_max_f32_e32 v58, 0, v58
	v_cvt_pk_bf16_f32 v77, v80, v77
	global_store_dwordx4 v[78:79], v[74:77], off
	s_nop 1
	v_mul_f32_e32 v71, v67, v67
	v_max_f32_e32 v67, v72, v72
	v_mul_f32_e32 v72, v68, v68
	v_cvt_pk_bf16_f32 v66, v0, v66
	v_max_f32_e32 v0, v62, v62
	v_mul_f32_e32 v62, v58, v58
	v_max_f32_e32 v59, 0, v59
	v_max_f32_e32 v60, 0, v60
	v_max_f32_e32 v67, 0, v67
	v_max_f32_e32 v68, 0, v73
	v_max_f32_e32 v69, 0, v69
	v_max_f32_e32 v0, 0, v0
	v_max_f32_e32 v58, 0, v63
	v_mul_f32_e32 v63, v59, v59
	v_max_f32_e32 v59, v64, v64
	v_mul_f32_e32 v64, v60, v60
	v_mul_f32_e32 v67, v67, v67
	v_mul_f32_e32 v68, v68, v68
	v_mul_f32_e32 v69, v69, v69
	v_mul_f32_e32 v0, v0, v0
	v_mul_f32_e32 v58, v58, v58
	v_max_f32_e32 v59, 0, v59
	v_max_f32_e32 v60, 0, v65
	v_max_f32_e32 v50, 0, v50
	v_cvt_pk_bf16_f32 v67, v67, v68
	v_cvt_pk_bf16_f32 v68, v70, v71
	v_cvt_pk_bf16_f32 v69, v72, v69
	global_store_dwordx4 v[78:79], v[66:69], off offset:256
	s_nop 1
	v_mul_f32_e32 v59, v59, v59
	v_mul_f32_e32 v60, v60, v60
	v_cvt_pk_bf16_f32 v58, v0, v58
	s_mov_b32 s6, 0x200000
	v_max_f32_e32 v0, v54, v54
	v_mul_f32_e32 v54, v50, v50
	v_max_f32_e32 v61, 0, v61
	v_cvt_pk_bf16_f32 v59, v59, v60
	v_cvt_pk_bf16_f32 v60, v62, v63
	v_add_co_u32_e32 v62, vcc, s6, v142
	v_max_f32_e32 v0, 0, v0
	v_max_f32_e32 v50, 0, v55
	v_mul_f32_e32 v61, v61, v61
	v_addc_co_u32_e32 v63, vcc, 0, v143, vcc
	v_mul_f32_e32 v0, v0, v0
	v_max_f32_e32 v51, 0, v51
	v_mul_f32_e32 v50, v50, v50
	v_max_f32_e32 v52, 0, v52
	v_max_f32_e32 v42, 0, v42
	v_cvt_pk_bf16_f32 v61, v64, v61
	global_store_dwordx4 v[62:63], v[58:61], off
	s_nop 1
	v_mul_f32_e32 v55, v51, v51
	v_max_f32_e32 v51, v56, v56
	v_mul_f32_e32 v56, v52, v52
	v_cvt_pk_bf16_f32 v50, v0, v50
	v_max_f32_e32 v0, v46, v46
	v_mul_f32_e32 v46, v42, v42
	v_max_f32_e32 v43, 0, v43
	v_max_f32_e32 v44, 0, v44
	v_max_f32_e32 v51, 0, v51
	v_max_f32_e32 v52, 0, v57
	v_max_f32_e32 v53, 0, v53
	v_max_f32_e32 v0, 0, v0
	v_max_f32_e32 v42, 0, v47
	v_mul_f32_e32 v47, v43, v43
	v_max_f32_e32 v43, v48, v48
	v_mul_f32_e32 v48, v44, v44
	v_mul_f32_e32 v51, v51, v51
	v_mul_f32_e32 v52, v52, v52
	v_mul_f32_e32 v53, v53, v53
	v_mul_f32_e32 v0, v0, v0
	v_mul_f32_e32 v42, v42, v42
	v_max_f32_e32 v43, 0, v43
	v_max_f32_e32 v44, 0, v49
	v_max_f32_e32 v34, 0, v34
	v_cvt_pk_bf16_f32 v51, v51, v52
	v_cvt_pk_bf16_f32 v52, v54, v55
	v_cvt_pk_bf16_f32 v53, v56, v53
	global_store_dwordx4 v[62:63], v[50:53], off offset:256
	s_nop 1
	v_mul_f32_e32 v43, v43, v43
	v_mul_f32_e32 v44, v44, v44
	v_cvt_pk_bf16_f32 v42, v0, v42
	s_mov_b32 s6, 0x240000
	v_max_f32_e32 v0, v38, v38
	v_mul_f32_e32 v38, v34, v34
	v_max_f32_e32 v45, 0, v45
	v_cvt_pk_bf16_f32 v43, v43, v44
	v_cvt_pk_bf16_f32 v44, v46, v47
	v_add_co_u32_e32 v46, vcc, s6, v142
	v_max_f32_e32 v0, 0, v0
	v_max_f32_e32 v34, 0, v39
	v_mul_f32_e32 v45, v45, v45
	v_addc_co_u32_e32 v47, vcc, 0, v143, vcc
	v_mul_f32_e32 v0, v0, v0
	v_max_f32_e32 v35, 0, v35
	v_mul_f32_e32 v34, v34, v34
	v_max_f32_e32 v36, 0, v36
	v_max_f32_e32 v26, 0, v26
	v_cvt_pk_bf16_f32 v45, v48, v45
	global_store_dwordx4 v[46:47], v[42:45], off
	s_nop 1
	v_mul_f32_e32 v39, v35, v35
	v_max_f32_e32 v35, v40, v40
	v_mul_f32_e32 v40, v36, v36
	v_cvt_pk_bf16_f32 v34, v0, v34
	v_max_f32_e32 v0, v30, v30
	v_mul_f32_e32 v30, v26, v26
	v_max_f32_e32 v27, 0, v27
	v_max_f32_e32 v28, 0, v28
	v_max_f32_e32 v35, 0, v35
	v_max_f32_e32 v36, 0, v41
	v_max_f32_e32 v37, 0, v37
	v_max_f32_e32 v0, 0, v0
	v_max_f32_e32 v26, 0, v31
	v_mul_f32_e32 v31, v27, v27
	v_max_f32_e32 v27, v32, v32
	v_mul_f32_e32 v32, v28, v28
	v_mul_f32_e32 v35, v35, v35
	v_mul_f32_e32 v36, v36, v36
	v_mul_f32_e32 v37, v37, v37
	v_mul_f32_e32 v0, v0, v0
	v_mul_f32_e32 v26, v26, v26
	v_max_f32_e32 v27, 0, v27
	v_max_f32_e32 v28, 0, v33
	v_max_f32_e32 v18, 0, v18
	v_cvt_pk_bf16_f32 v35, v35, v36
	v_cvt_pk_bf16_f32 v36, v38, v39
	v_cvt_pk_bf16_f32 v37, v40, v37
	global_store_dwordx4 v[46:47], v[34:37], off offset:256
	s_nop 1
	v_mul_f32_e32 v27, v27, v27
	v_mul_f32_e32 v28, v28, v28
	v_cvt_pk_bf16_f32 v26, v0, v26
	s_mov_b32 s6, 0x280000
	v_max_f32_e32 v0, v22, v22
	v_mul_f32_e32 v22, v18, v18
	v_max_f32_e32 v29, 0, v29
	v_cvt_pk_bf16_f32 v27, v27, v28
	v_cvt_pk_bf16_f32 v28, v30, v31
	v_add_co_u32_e32 v30, vcc, s6, v142
	v_max_f32_e32 v0, 0, v0
	v_max_f32_e32 v18, 0, v23
	v_mul_f32_e32 v29, v29, v29
	v_addc_co_u32_e32 v31, vcc, 0, v143, vcc
	v_mul_f32_e32 v0, v0, v0
	v_max_f32_e32 v19, 0, v19
	v_mul_f32_e32 v18, v18, v18
	v_max_f32_e32 v20, 0, v20
	v_max_f32_e32 v10, 0, v10
	v_max_f32_e32 v11, 0, v11
	v_max_f32_e32 v12, 0, v12
	v_cvt_pk_bf16_f32 v29, v32, v29
	global_store_dwordx4 v[30:31], v[26:29], off
	s_nop 1
	v_mul_f32_e32 v23, v19, v19
	v_max_f32_e32 v19, v24, v24
	v_mul_f32_e32 v24, v20, v20
	v_cvt_pk_bf16_f32 v18, v0, v18
	v_max_f32_e32 v0, v14, v14
	v_mul_f32_e32 v14, v10, v10
	v_max_f32_e32 v10, v15, v15
	v_mul_f32_e32 v15, v11, v11
	v_max_f32_e32 v11, v16, v16
	v_mul_f32_e32 v16, v12, v12
	v_max_f32_e32 v19, 0, v19
	v_max_f32_e32 v20, 0, v25
	v_max_f32_e32 v21, 0, v21
	v_max_f32_e32 v0, 0, v0
	v_max_f32_e32 v10, 0, v10
	v_max_f32_e32 v11, 0, v11
	v_max_f32_e32 v12, 0, v17
	v_mul_f32_e32 v19, v19, v19
	v_mul_f32_e32 v20, v20, v20
	v_mul_f32_e32 v21, v21, v21
	v_mul_f32_e32 v0, v0, v0
	v_mul_f32_e32 v10, v10, v10
	v_mul_f32_e32 v11, v11, v11
	v_mul_f32_e32 v12, v12, v12
	s_mov_b32 s6, 0x2c0000
	v_max_f32_e32 v2, 0, v2
	v_max_f32_e32 v3, 0, v3
	v_max_f32_e32 v4, 0, v4
	v_cvt_pk_bf16_f32 v19, v19, v20
	v_cvt_pk_bf16_f32 v20, v22, v23
	v_cvt_pk_bf16_f32 v21, v24, v21
	global_store_dwordx4 v[30:31], v[18:21], off offset:256
	s_nop 1
	v_cvt_pk_bf16_f32 v10, v0, v10
	v_cvt_pk_bf16_f32 v11, v11, v12
	v_cvt_pk_bf16_f32 v12, v14, v15
	v_add_co_u32_e32 v14, vcc, s6, v142
	v_max_f32_e32 v0, v6, v6
	v_mul_f32_e32 v6, v2, v2
	v_max_f32_e32 v2, v7, v7
	v_mul_f32_e32 v7, v3, v3
	v_max_f32_e32 v3, v8, v8
	v_mul_f32_e32 v8, v4, v4
	v_max_f32_e32 v13, 0, v13
	v_addc_co_u32_e32 v15, vcc, 0, v143, vcc
	v_max_f32_e32 v2, 0, v2
	v_max_f32_e32 v3, 0, v3
	v_max_f32_e32 v4, 0, v9
	v_max_f32_e32 v5, 0, v5
	v_mul_f32_e32 v13, v13, v13
	v_max_f32_e32 v0, 0, v0
	v_mul_f32_e32 v2, v2, v2
	v_mul_f32_e32 v3, v3, v3
	v_mul_f32_e32 v4, v4, v4
	v_mul_f32_e32 v5, v5, v5
	s_andn2_b64 vcc, exec, s[40:41]
	s_mov_b64 s[6:7], -1
	s_mov_b32 s70, 0x2aaaaaab
	s_mov_b64 s[72:73], 0x26000
	v_cvt_pk_bf16_f32 v13, v16, v13
	global_store_dwordx4 v[14:15], v[10:13], off
	s_nop 1
	v_mul_f32_e32 v0, v0, v0
	v_cvt_pk_bf16_f32 v2, v0, v2
	v_cvt_pk_bf16_f32 v3, v3, v4
	v_cvt_pk_bf16_f32 v4, v6, v7
	v_cvt_pk_bf16_f32 v5, v8, v5
	global_store_dwordx4 v[14:15], v[2:5], off offset:256
	s_nop 1
	s_cbranch_vccnz .LBB0_28
	s_andn2_b64 vcc, exec, s[28:29]
	s_cbranch_vccnz .LBB0_27
	s_barrier
	s_branch .LBB0_27
.Lgw1a_r:
	s_waitcnt vmcnt(24)
	s_branch .Lgw1a_d
.Lgw1b_r:
	s_waitcnt vmcnt(24)
	s_mov_b32 s98, 0
	s_branch .Lgw1b_d

.LBB0_166:
	v_mov_b32_e32 v135, v1
	v_lshl_add_u64 v[8:9], s[10:11], 0, v[134:135]
	v_mov_b32_e32 v131, v1
	v_lshl_add_u64 v[10:11], s[10:11], 0, v[130:131]
	v_mov_b32_e32 v137, v1
	s_add_i32 m0, s58, 0x18000
	v_lshl_add_u64 v[8:9], v[8:9], 0, s[34:35]
	v_lshl_add_u64 v[16:17], s[8:9], 0, v[136:137]
	v_mov_b32_e32 v133, v1
	s_waitcnt vmcnt(2)
	s_barrier
	global_load_lds_dwordx4 v[8:9], off
	v_lshl_add_u64 v[8:9], v[10:11], 0, s[34:35]
	s_add_i32 m0, s58, 0x1a000
	s_add_i32 s66, s58, 0x8000
	v_lshl_add_u64 v[18:19], s[8:9], 0, v[132:133]
	global_load_lds_dwordx4 v[8:9], off
	v_lshl_add_u64 v[8:9], v[16:17], 0, s[34:35]
	s_mov_b32 m0, s66
	s_add_i32 s67, s58, 0xa000
	v_lshl_add_u64 v[12:13], s[12:13], 0, v[134:135]
	global_load_lds_dwordx4 v[8:9], off
	v_lshl_add_u64 v[8:9], v[18:19], 0, s[34:35]
	s_mov_b32 m0, s67
	v_lshl_add_u64 v[14:15], s[12:13], 0, v[130:131]
	global_load_lds_dwordx4 v[8:9], off
	s_add_i32 m0, s58, 0x1c000
	v_lshl_add_u64 v[8:9], v[12:13], 0, s[34:35]
	global_load_lds_dwordx4 v[8:9], off
	v_lshl_add_u64 v[8:9], v[14:15], 0, s[34:35]
	s_add_i32 m0, s58, 0x1e000
	v_and_b32_e32 v20, 48, v0
	global_load_lds_dwordx4 v[8:9], off
	s_lshr_b32 s7, s7, 26
	v_lshlrev_b32_e32 v21, 6, v0
	s_movk_i32 s13, 0x3c0
	s_add_i32 s7, s6, s7
	v_and_or_b32 v20, v21, s13, v20
	v_lshlrev_b32_e32 v21, 2, v0
	s_and_b32 s12, s16, 3
	s_ashr_i32 s64, s7, 6
	s_lshl_b32 s7, s15, 13
	v_and_b32_e32 v21, 32, v21
	s_lshl_b32 s65, s15, 6
	v_bitop3_b32 v22, v20, s7, v21 bitop3:0xde
	s_lshl_b32 s7, s12, 12
	v_and_b32_e32 v143, 63, v0
	v_add_u32_e32 v0, v7, v5
	s_cmp_gt_i32 s6, 63
	v_add_lshl_u32 v0, v0, v6, 1
	s_waitcnt vmcnt(6)
	s_cselect_b64 s[52:53], -1, 0
	s_add_i32 s68, s64, -2
	v_lshl_add_u64 v[138:139], s[28:29], 0, v[0:1]
	v_add_u32_e32 v0, v4, v2
	s_cmpk_lt_u32 s14, 0x100
	v_add_lshl_u32 v0, v0, v3, 1
	v_bitop3_b32 v142, v20, s7, v21 bitop3:0xde
	s_cselect_b64 s[54:55], -1, 0
	s_lshl_b32 s70, s12, 6
	v_lshl_add_u64 v[140:141], s[28:29], 0, v[0:1]
	s_mov_b32 s72, 0
	v_add_u32_e32 v144, 0, v22
	v_readlane_b32 s14, v254, 31
	v_readlane_b32 s6, v254, 34
	s_barrier
	s_mov_b32 s98, 0
	s_branch .LBB0_169

.LBB0_177:
	s_add_i32 s13, s10, 2
	s_add_u32 s15, s8, 0x80
	s_addc_u32 s11, s9, 0
	s_add_i32 s38, 0, 0x10000
	s_cmp_eq_u32 s68, s10
	s_cselect_b32 s11, s43, s11
	s_cselect_b32 s10, s42, s15
	v_add_u32_e32 v0, s38, v142
	s_cselect_b32 s17, s57, s12
	s_cselect_b32 s16, s56, s7
	s_add_i32 s15, 0, 0x14000
	ds_read_b128 v[146:149], v0
	ds_read_b128 v[150:153], v0 offset:1024
	ds_read_b128 v[154:157], v0 offset:2048
	ds_read_b128 v[158:161], v0 offset:3072
	v_add_u32_e32 v0, s15, v142
	ds_read_b128 v[166:169], v0
	ds_read_b128 v[170:173], v0 offset:1024
	ds_read_b128 v[174:177], v0 offset:2048
	ds_read_b128 v[178:181], v0 offset:3072
	v_lshl_add_u64 v[214:215], s[8:9], 0, v[138:139]
	s_add_i32 m0, s58, 0xc000
	ds_read_b128 v[182:185], v144
	ds_read_b128 v[186:189], v144 offset:1024
	ds_read_b128 v[190:193], v144 offset:2048
	ds_read_b128 v[194:197], v144 offset:3072
	ds_read_b128 v[198:201], v144 offset:4096
	ds_read_b128 v[202:205], v144 offset:5120
	ds_read_b128 v[206:209], v144 offset:6144
	ds_read_b128 v[210:213], v144 offset:7168
	global_load_lds_dwordx4 v[214:215], off
	v_lshl_add_u64 v[214:215], s[8:9], 0, v[140:141]
	s_add_i32 m0, s58, 0xe000
	s_nop 0
	global_load_lds_dwordx4 v[214:215], off
	s_cmp_lg_u32 s98, 0
	s_cbranch_scc1 .Lgw2a_r
	s_waitcnt vmcnt(8)
.Lgw2a_d:
	s_waitcnt lgkmcnt(0)
	s_barrier
	s_setprio 1
	s_waitcnt lgkmcnt(0)
	v_mfma_f32_16x16x32_bf16 v[122:125], v[146:149], v[182:185], v[122:125]
	v_mfma_f32_16x16x32_bf16 v[126:129], v[154:157], v[182:185], v[126:129]
	v_mfma_f32_16x16x32_bf16 v[118:121], v[146:149], v[190:193], v[118:121]
	v_mfma_f32_16x16x32_bf16 v[114:117], v[154:157], v[190:193], v[114:117]
	v_mfma_f32_16x16x32_bf16 v[110:113], v[146:149], v[198:201], v[110:113]
	v_mfma_f32_16x16x32_bf16 v[106:109], v[154:157], v[198:201], v[106:109]
	v_mfma_f32_16x16x32_bf16 v[102:105], v[146:149], v[206:209], v[102:105]
	v_mfma_f32_16x16x32_bf16 v[98:101], v[154:157], v[206:209], v[98:101]
	v_mfma_f32_16x16x32_bf16 v[122:125], v[150:153], v[186:189], v[122:125]
	v_mfma_f32_16x16x32_bf16 v[126:129], v[158:161], v[186:189], v[126:129]
	v_mfma_f32_16x16x32_bf16 v[118:121], v[150:153], v[194:197], v[118:121]
	v_mfma_f32_16x16x32_bf16 v[114:117], v[158:161], v[194:197], v[114:117]
	v_mfma_f32_16x16x32_bf16 v[110:113], v[150:153], v[202:205], v[110:113]
	v_mfma_f32_16x16x32_bf16 v[106:109], v[158:161], v[202:205], v[106:109]
	v_mfma_f32_16x16x32_bf16 v[102:105], v[150:153], v[210:213], v[102:105]
	v_mfma_f32_16x16x32_bf16 v[98:101], v[158:161], v[210:213], v[98:101]
	s_setprio 0
	s_setprio 1
	v_mfma_f32_16x16x32_bf16 v[62:65], v[166:169], v[182:185], v[62:65]
	v_mfma_f32_16x16x32_bf16 v[58:61], v[174:177], v[182:185], v[58:61]
	v_mfma_f32_16x16x32_bf16 v[54:57], v[166:169], v[190:193], v[54:57]
	v_mfma_f32_16x16x32_bf16 v[50:53], v[174:177], v[190:193], v[50:53]
	v_mfma_f32_16x16x32_bf16 v[46:49], v[166:169], v[198:201], v[46:49]
	v_mfma_f32_16x16x32_bf16 v[42:45], v[174:177], v[198:201], v[42:45]
	v_mfma_f32_16x16x32_bf16 v[38:41], v[166:169], v[206:209], v[38:41]
	v_mfma_f32_16x16x32_bf16 v[34:37], v[174:177], v[206:209], v[34:37]
	v_mfma_f32_16x16x32_bf16 v[62:65], v[170:173], v[186:189], v[62:65]
	v_mfma_f32_16x16x32_bf16 v[58:61], v[178:181], v[186:189], v[58:61]
	v_mfma_f32_16x16x32_bf16 v[54:57], v[170:173], v[194:197], v[54:57]
	v_mfma_f32_16x16x32_bf16 v[50:53], v[178:181], v[194:197], v[50:53]
	v_mfma_f32_16x16x32_bf16 v[46:49], v[170:173], v[202:205], v[46:49]
	v_mfma_f32_16x16x32_bf16 v[42:45], v[178:181], v[202:205], v[42:45]
	v_mfma_f32_16x16x32_bf16 v[38:41], v[170:173], v[210:213], v[38:41]
	v_mfma_f32_16x16x32_bf16 v[34:37], v[178:181], v[210:213], v[34:37]
	s_setprio 0
	s_barrier
	s_add_i32 s38, s38, s49
	v_lshl_add_u64 v[214:215], s[16:17], 0, v[134:135]
	s_mov_b32 m0, s38
	ds_read_b128 v[182:185], v144 offset:16384
	ds_read_b128 v[186:189], v144 offset:17408
	ds_read_b128 v[190:193], v144 offset:18432
	ds_read_b128 v[194:197], v144 offset:19456
	ds_read_b128 v[198:201], v144 offset:20480
	ds_read_b128 v[202:205], v144 offset:21504
	ds_read_b128 v[206:209], v144 offset:22528
	ds_read_b128 v[210:213], v144 offset:23552
	global_load_lds_dwordx4 v[214:215], off
	s_add_i32 m0, s38, 0x2000
	v_lshl_add_u64 v[216:217], s[16:17], 0, v[130:131]
	s_add_u32 s16, s16, s28
	s_addc_u32 s17, s17, s29
	s_add_i32 s15, s15, s49
	global_load_lds_dwordx4 v[216:217], off
	v_lshl_add_u64 v[218:219], s[16:17], 0, v[134:135]
	s_mov_b32 m0, s15
	v_lshl_add_u64 v[220:221], s[16:17], 0, v[130:131]
	global_load_lds_dwordx4 v[218:219], off
	s_add_i32 m0, s15, 0x2000
	v_lshl_add_u64 v[222:223], s[10:11], 0, v[136:137]
	global_load_lds_dwordx4 v[220:221], off
	s_mov_b32 m0, s58
	v_lshl_add_u64 v[236:237], s[10:11], 0, v[132:133]
	global_load_lds_dwordx4 v[222:223], off
	s_mov_b32 m0, s59
	s_nop 0
	global_load_lds_dwordx4 v[236:237], off
	s_cmp_lg_u32 s98, 0
	s_cbranch_scc1 .Lgw2b_r
	s_waitcnt vmcnt(8)
.Lgw2b_d:
	s_waitcnt lgkmcnt(0)
	s_barrier
	s_setprio 1
	s_waitcnt lgkmcnt(0)
	v_mfma_f32_16x16x32_bf16 v[94:97], v[146:149], v[182:185], v[94:97]
	v_mfma_f32_16x16x32_bf16 v[90:93], v[154:157], v[182:185], v[90:93]
	v_mfma_f32_16x16x32_bf16 v[86:89], v[146:149], v[190:193], v[86:89]
	v_mfma_f32_16x16x32_bf16 v[82:85], v[154:157], v[190:193], v[82:85]
	v_mfma_f32_16x16x32_bf16 v[78:81], v[146:149], v[198:201], v[78:81]
	v_mfma_f32_16x16x32_bf16 v[74:77], v[154:157], v[198:201], v[74:77]
	v_mfma_f32_16x16x32_bf16 v[70:73], v[146:149], v[206:209], v[70:73]
	v_mfma_f32_16x16x32_bf16 v[66:69], v[154:157], v[206:209], v[66:69]
	v_mfma_f32_16x16x32_bf16 v[94:97], v[150:153], v[186:189], v[94:97]
	v_mfma_f32_16x16x32_bf16 v[90:93], v[158:161], v[186:189], v[90:93]
	v_mfma_f32_16x16x32_bf16 v[86:89], v[150:153], v[194:197], v[86:89]
	v_mfma_f32_16x16x32_bf16 v[82:85], v[158:161], v[194:197], v[82:85]
	v_mfma_f32_16x16x32_bf16 v[78:81], v[150:153], v[202:205], v[78:81]
	v_mfma_f32_16x16x32_bf16 v[74:77], v[158:161], v[202:205], v[74:77]
	v_mfma_f32_16x16x32_bf16 v[70:73], v[150:153], v[210:213], v[70:73]
	v_mfma_f32_16x16x32_bf16 v[66:69], v[158:161], v[210:213], v[66:69]
	s_setprio 0
	s_setprio 1
	v_mfma_f32_16x16x32_bf16 v[30:33], v[166:169], v[182:185], v[30:33]
	v_mfma_f32_16x16x32_bf16 v[26:29], v[174:177], v[182:185], v[26:29]
	v_mfma_f32_16x16x32_bf16 v[22:25], v[166:169], v[190:193], v[22:25]
	v_mfma_f32_16x16x32_bf16 v[18:21], v[174:177], v[190:193], v[18:21]
	v_mfma_f32_16x16x32_bf16 v[14:17], v[166:169], v[198:201], v[14:17]
	v_mfma_f32_16x16x32_bf16 v[10:13], v[174:177], v[198:201], v[10:13]
	v_mfma_f32_16x16x32_bf16 v[6:9], v[166:169], v[206:209], v[6:9]
	v_mfma_f32_16x16x32_bf16 v[2:5], v[174:177], v[206:209], v[2:5]
	v_mfma_f32_16x16x32_bf16 v[30:33], v[170:173], v[186:189], v[30:33]
	v_mfma_f32_16x16x32_bf16 v[26:29], v[178:181], v[186:189], v[26:29]
	v_mfma_f32_16x16x32_bf16 v[22:25], v[170:173], v[194:197], v[22:25]
	v_mfma_f32_16x16x32_bf16 v[18:21], v[178:181], v[194:197], v[18:21]
	v_mfma_f32_16x16x32_bf16 v[14:17], v[170:173], v[202:205], v[14:17]
	v_mfma_f32_16x16x32_bf16 v[10:13], v[178:181], v[202:205], v[10:13]
	v_mfma_f32_16x16x32_bf16 v[6:9], v[170:173], v[210:213], v[6:9]
	v_mfma_f32_16x16x32_bf16 v[2:5], v[178:181], v[210:213], v[2:5]
	s_setprio 0
	s_barrier
	s_add_i32 s15, 0, 0x18000
	v_add_u32_e32 v0, s15, v142
	s_add_i32 s16, 0, 0x1c000
	ds_read_b128 v[146:149], v0
	ds_read_b128 v[150:153], v0 offset:1024
	ds_read_b128 v[154:157], v0 offset:2048
	ds_read_b128 v[158:161], v0 offset:3072
	v_add_u32_e32 v0, s16, v142
	ds_read_b128 v[166:169], v0
	ds_read_b128 v[170:173], v0 offset:1024
	ds_read_b128 v[174:177], v0 offset:2048
	ds_read_b128 v[178:181], v0 offset:3072
	s_add_u32 s10, s10, s28
	s_addc_u32 s11, s11, s29
	s_mov_b32 m0, s62
	v_lshl_add_u64 v[238:239], s[10:11], 0, v[136:137]
	ds_read_b128 v[182:185], v144 offset:32768
	ds_read_b128 v[186:189], v144 offset:33792
	ds_read_b128 v[190:193], v144 offset:34816
	ds_read_b128 v[194:197], v144 offset:35840
	ds_read_b128 v[198:201], v144 offset:36864
	ds_read_b128 v[202:205], v144 offset:37888
	ds_read_b128 v[206:209], v144 offset:38912
	ds_read_b128 v[210:213], v144 offset:39936
	global_load_lds_dwordx4 v[238:239], off
	v_lshl_add_u64 v[238:239], s[10:11], 0, v[132:133]
	s_mov_b32 m0, s63
	s_nop 0
	global_load_lds_dwordx4 v[238:239], off
	s_waitcnt vmcnt(8)
	s_waitcnt lgkmcnt(0)
	s_barrier
	s_setprio 1
	s_waitcnt lgkmcnt(0)
	v_mfma_f32_16x16x32_bf16 v[122:125], v[146:149], v[182:185], v[122:125]
	v_mfma_f32_16x16x32_bf16 v[126:129], v[154:157], v[182:185], v[126:129]
	v_mfma_f32_16x16x32_bf16 v[118:121], v[146:149], v[190:193], v[118:121]
	v_mfma_f32_16x16x32_bf16 v[114:117], v[154:157], v[190:193], v[114:117]
	v_mfma_f32_16x16x32_bf16 v[110:113], v[146:149], v[198:201], v[110:113]
	v_mfma_f32_16x16x32_bf16 v[106:109], v[154:157], v[198:201], v[106:109]
	v_mfma_f32_16x16x32_bf16 v[102:105], v[146:149], v[206:209], v[102:105]
	v_mfma_f32_16x16x32_bf16 v[98:101], v[154:157], v[206:209], v[98:101]
	v_mfma_f32_16x16x32_bf16 v[122:125], v[150:153], v[186:189], v[122:125]
	v_mfma_f32_16x16x32_bf16 v[126:129], v[158:161], v[186:189], v[126:129]
	v_mfma_f32_16x16x32_bf16 v[118:121], v[150:153], v[194:197], v[118:121]
	v_mfma_f32_16x16x32_bf16 v[114:117], v[158:161], v[194:197], v[114:117]
	v_mfma_f32_16x16x32_bf16 v[110:113], v[150:153], v[202:205], v[110:113]
	v_mfma_f32_16x16x32_bf16 v[106:109], v[158:161], v[202:205], v[106:109]
	v_mfma_f32_16x16x32_bf16 v[102:105], v[150:153], v[210:213], v[102:105]
	v_mfma_f32_16x16x32_bf16 v[98:101], v[158:161], v[210:213], v[98:101]
	s_setprio 0
	s_setprio 1
	v_mfma_f32_16x16x32_bf16 v[62:65], v[166:169], v[182:185], v[62:65]
	v_mfma_f32_16x16x32_bf16 v[58:61], v[174:177], v[182:185], v[58:61]
	v_mfma_f32_16x16x32_bf16 v[54:57], v[166:169], v[190:193], v[54:57]
	v_mfma_f32_16x16x32_bf16 v[50:53], v[174:177], v[190:193], v[50:53]
	v_mfma_f32_16x16x32_bf16 v[46:49], v[166:169], v[198:201], v[46:49]
	v_mfma_f32_16x16x32_bf16 v[42:45], v[174:177], v[198:201], v[42:45]
	v_mfma_f32_16x16x32_bf16 v[38:41], v[166:169], v[206:209], v[38:41]
	v_mfma_f32_16x16x32_bf16 v[34:37], v[174:177], v[206:209], v[34:37]
	v_mfma_f32_16x16x32_bf16 v[62:65], v[170:173], v[186:189], v[62:65]
	v_mfma_f32_16x16x32_bf16 v[58:61], v[178:181], v[186:189], v[58:61]
	v_mfma_f32_16x16x32_bf16 v[54:57], v[170:173], v[194:197], v[54:57]
	v_mfma_f32_16x16x32_bf16 v[50:53], v[178:181], v[194:197], v[50:53]
	v_mfma_f32_16x16x32_bf16 v[46:49], v[170:173], v[202:205], v[46:49]
	v_mfma_f32_16x16x32_bf16 v[42:45], v[178:181], v[202:205], v[42:45]
	v_mfma_f32_16x16x32_bf16 v[38:41], v[170:173], v[210:213], v[38:41]
	v_mfma_f32_16x16x32_bf16 v[34:37], v[178:181], v[210:213], v[34:37]
	s_setprio 0
	s_barrier
	s_add_i32 s10, s15, s49
	v_lshl_add_u64 v[214:215], v[214:215], 0, s[34:35]
	s_mov_b32 m0, s10
	ds_read_b128 v[182:185], v144 offset:49152
	ds_read_b128 v[186:189], v144 offset:50176
	ds_read_b128 v[190:193], v144 offset:51200
	ds_read_b128 v[194:197], v144 offset:52224
	ds_read_b128 v[198:201], v144 offset:53248
	ds_read_b128 v[202:205], v144 offset:54272
	ds_read_b128 v[206:209], v144 offset:55296
	ds_read_b128 v[210:213], v144 offset:56320
	global_load_lds_dwordx4 v[214:215], off
	v_lshl_add_u64 v[214:215], v[216:217], 0, s[34:35]
	s_add_i32 m0, s10, 0x2000
	s_add_i32 s10, s16, s49
	global_load_lds_dwordx4 v[214:215], off
	v_lshl_add_u64 v[214:215], v[218:219], 0, s[34:35]
	s_mov_b32 m0, s10
	s_nop 0
	global_load_lds_dwordx4 v[214:215], off
	v_lshl_add_u64 v[214:215], v[220:221], 0, s[34:35]
	s_add_i32 m0, s10, 0x2000
	s_nop 0
	global_load_lds_dwordx4 v[214:215], off
	v_lshl_add_u64 v[214:215], v[222:223], 0, s[34:35]
	s_mov_b32 m0, s66
	s_nop 0
	global_load_lds_dwordx4 v[214:215], off
	v_lshl_add_u64 v[214:215], v[236:237], 0, s[34:35]
	s_mov_b32 m0, s67
	s_nop 0
	global_load_lds_dwordx4 v[214:215], off
	s_waitcnt vmcnt(8)
	s_waitcnt lgkmcnt(0)
	s_barrier
	s_setprio 1
	s_waitcnt lgkmcnt(0)
	v_mfma_f32_16x16x32_bf16 v[94:97], v[146:149], v[182:185], v[94:97]
	v_mfma_f32_16x16x32_bf16 v[90:93], v[154:157], v[182:185], v[90:93]
	v_mfma_f32_16x16x32_bf16 v[86:89], v[146:149], v[190:193], v[86:89]
	v_mfma_f32_16x16x32_bf16 v[82:85], v[154:157], v[190:193], v[82:85]
	v_mfma_f32_16x16x32_bf16 v[78:81], v[146:149], v[198:201], v[78:81]
	v_mfma_f32_16x16x32_bf16 v[74:77], v[154:157], v[198:201], v[74:77]
	v_mfma_f32_16x16x32_bf16 v[70:73], v[146:149], v[206:209], v[70:73]
	v_mfma_f32_16x16x32_bf16 v[66:69], v[154:157], v[206:209], v[66:69]
	v_mfma_f32_16x16x32_bf16 v[94:97], v[150:153], v[186:189], v[94:97]
	v_mfma_f32_16x16x32_bf16 v[90:93], v[158:161], v[186:189], v[90:93]
	v_mfma_f32_16x16x32_bf16 v[86:89], v[150:153], v[194:197], v[86:89]
	v_mfma_f32_16x16x32_bf16 v[82:85], v[158:161], v[194:197], v[82:85]
	v_mfma_f32_16x16x32_bf16 v[78:81], v[150:153], v[202:205], v[78:81]
	v_mfma_f32_16x16x32_bf16 v[74:77], v[158:161], v[202:205], v[74:77]
	v_mfma_f32_16x16x32_bf16 v[70:73], v[150:153], v[210:213], v[70:73]
	v_mfma_f32_16x16x32_bf16 v[66:69], v[158:161], v[210:213], v[66:69]
	s_setprio 0
	s_setprio 1
	v_mfma_f32_16x16x32_bf16 v[30:33], v[166:169], v[182:185], v[30:33]
	v_mfma_f32_16x16x32_bf16 v[26:29], v[174:177], v[182:185], v[26:29]
	v_mfma_f32_16x16x32_bf16 v[22:25], v[166:169], v[190:193], v[22:25]
	v_mfma_f32_16x16x32_bf16 v[18:21], v[174:177], v[190:193], v[18:21]
	v_mfma_f32_16x16x32_bf16 v[14:17], v[166:169], v[198:201], v[14:17]
	v_mfma_f32_16x16x32_bf16 v[10:13], v[174:177], v[198:201], v[10:13]
	v_mfma_f32_16x16x32_bf16 v[6:9], v[166:169], v[206:209], v[6:9]
	v_mfma_f32_16x16x32_bf16 v[2:5], v[174:177], v[206:209], v[2:5]
	v_mfma_f32_16x16x32_bf16 v[30:33], v[170:173], v[186:189], v[30:33]
	v_mfma_f32_16x16x32_bf16 v[26:29], v[178:181], v[186:189], v[26:29]
	v_mfma_f32_16x16x32_bf16 v[22:25], v[170:173], v[194:197], v[22:25]
	v_mfma_f32_16x16x32_bf16 v[18:21], v[178:181], v[194:197], v[18:21]
	v_mfma_f32_16x16x32_bf16 v[14:17], v[170:173], v[202:205], v[14:17]
	v_mfma_f32_16x16x32_bf16 v[10:13], v[178:181], v[202:205], v[10:13]
	v_mfma_f32_16x16x32_bf16 v[6:9], v[170:173], v[210:213], v[6:9]
	v_mfma_f32_16x16x32_bf16 v[2:5], v[178:181], v[210:213], v[2:5]
	s_setprio 0
	s_barrier
	s_add_u32 s8, s8, 0x100
	s_addc_u32 s9, s9, 0
	s_add_u32 s7, s7, 0x100
	s_addc_u32 s12, s12, 0
	s_cmp_ge_i32 s13, s64
	s_mov_b32 s10, s13
	s_cbranch_scc0 .LBB0_177

.LBB0_180:
	s_mov_b32 s98, 1
	s_lshl_b32 s7, s14, 1
	s_and_b32 s8, s7, 2
	s_ashr_i32 s7, s6, 31
	s_lshl_b64 s[6:7], s[6:7], 8
	s_cmp_lt_u32 s14, 2
	s_movk_i32 s9, 0x80
	s_cselect_b32 s79, 0xc0, s9
	s_mov_b32 s9, 0x25a00000
	s_cselect_b32 s9, s9, 0x27500000
	s_add_u32 s86, s60, s9
	s_addc_u32 s87, s61, 0
	s_mul_i32 s88, s8, 0x4800
	s_add_u32 s8, s6, s88
	s_addc_u32 s9, s7, 0
	v_mov_b32_e32 v0, v143
	s_mul_i32 s9, s9, s79
	s_mul_hi_u32 s10, s8, s79
	s_add_i32 s9, s10, s9
	v_and_or_b32 v145, v0, 15, s65
	s_mul_i32 s8, s8, s79
	v_mul_lo_u32 v145, s79, v145
	s_lshl_b64 s[8:9], s[8:9], 1
	v_lshlrev_b32_e32 v145, 1, v145
	v_and_b32_e32 v0, -16, v0
	s_add_u32 s8, s86, s8
	v_add3_u32 v0, v0, s70, v145
	s_addc_u32 s9, s87, s9
	v_lshl_add_u64 v[146:147], s[8:9], 0, v[0:1]
	v_cvt_pk_bf16_f32 v122, v122, v123
	v_cvt_pk_bf16_f32 v123, v124, v125
	v_cvt_pk_bf16_f32 v124, v126, v127
	v_cvt_pk_bf16_f32 v125, v128, v129
	global_store_dwordx4 v0, v[122:125], s[8:9]
	s_lshl_b32 s38, s79, 5
	s_lshl_b32 s8, s79, 6
	s_lshl_b32 s12, s79, 8
	s_addk_i32 s88, 0x4800
	v_cvt_pk_bf16_f32 v118, v118, v119
	v_cvt_pk_bf16_f32 v119, v120, v121
	v_cvt_pk_bf16_f32 v120, v114, v115
	v_lshl_add_u64 v[114:115], v[146:147], 0, s[38:39]
	s_mov_b32 s9, s39
	s_add_u32 s6, s6, s88
	v_cvt_pk_bf16_f32 v121, v116, v117
	global_store_dwordx4 v[114:115], v[118:121], off
	v_cvt_pk_bf16_f32 v110, v110, v111
	v_cvt_pk_bf16_f32 v111, v112, v113
	v_cvt_pk_bf16_f32 v112, v106, v107
	v_lshl_add_u64 v[106:107], v[146:147], 0, s[8:9]
	s_mul_i32 s10, s79, 0x60
	s_mov_b32 s11, s39
	s_addc_u32 s7, s7, 0
	v_cvt_pk_bf16_f32 v113, v108, v109
	global_store_dwordx4 v[106:107], v[110:113], off
	v_cvt_pk_bf16_f32 v102, v102, v103
	v_cvt_pk_bf16_f32 v103, v104, v105
	v_cvt_pk_bf16_f32 v104, v98, v99
	v_lshl_add_u64 v[98:99], v[146:147], 0, s[10:11]
	s_mov_b32 s13, s39
	s_mul_i32 s7, s7, s79
	s_mul_hi_u32 s88, s6, s79
	v_cvt_pk_bf16_f32 v105, v100, v101
	global_store_dwordx4 v[98:99], v[102:105], off
	v_cvt_pk_bf16_f32 v94, v94, v95
	v_cvt_pk_bf16_f32 v95, v96, v97
	v_cvt_pk_bf16_f32 v96, v90, v91
	v_lshl_add_u64 v[90:91], v[146:147], 0, s[12:13]
	s_mul_i32 s14, s79, 0x120
	s_mov_b32 s15, s39
	s_add_i32 s7, s88, s7
	s_mul_i32 s6, s6, s79
	v_cvt_pk_bf16_f32 v97, v92, v93
	global_store_dwordx4 v[90:91], v[94:97], off
	v_cvt_pk_bf16_f32 v86, v86, v87
	v_cvt_pk_bf16_f32 v87, v88, v89
	v_cvt_pk_bf16_f32 v88, v82, v83
	v_lshl_add_u64 v[82:83], v[146:147], 0, s[14:15]
	s_mul_i32 s16, s79, 0x140
	s_mov_b32 s17, s39
	s_lshl_b64 s[6:7], s[6:7], 1
	v_cvt_pk_bf16_f32 v89, v84, v85
	global_store_dwordx4 v[82:83], v[86:89], off
	v_cvt_pk_bf16_f32 v78, v78, v79
	v_cvt_pk_bf16_f32 v79, v80, v81
	v_cvt_pk_bf16_f32 v80, v74, v75
	v_lshl_add_u64 v[74:75], v[146:147], 0, s[16:17]
	s_mul_i32 s84, s79, 0x160
	s_mov_b32 s85, s39
	s_add_u32 s6, s86, s6
	v_cvt_pk_bf16_f32 v81, v76, v77
	global_store_dwordx4 v[74:75], v[78:81], off
	v_cvt_pk_bf16_f32 v70, v70, v71
	v_cvt_pk_bf16_f32 v71, v72, v73
	v_cvt_pk_bf16_f32 v72, v66, v67
	v_lshl_add_u64 v[66:67], v[146:147], 0, s[84:85]
	s_addc_u32 s7, s87, s7
	v_cvt_pk_bf16_f32 v73, v68, v69
	global_store_dwordx4 v[66:67], v[70:73], off
	v_lshl_add_u64 v[66:67], s[6:7], 0, v[0:1]
	v_cvt_pk_bf16_f32 v62, v62, v63
	v_cvt_pk_bf16_f32 v63, v64, v65
	v_cvt_pk_bf16_f32 v64, v58, v59
	v_cvt_pk_bf16_f32 v65, v60, v61
	global_store_dwordx4 v0, v[62:65], s[6:7]
	v_cvt_pk_bf16_f32 v54, v54, v55
	v_cvt_pk_bf16_f32 v55, v56, v57
	v_cvt_pk_bf16_f32 v56, v50, v51
	v_lshl_add_u64 v[50:51], v[66:67], 0, s[38:39]
	v_cvt_pk_bf16_f32 v57, v52, v53
	global_store_dwordx4 v[50:51], v[54:57], off
	v_cvt_pk_bf16_f32 v46, v46, v47
	v_cvt_pk_bf16_f32 v47, v48, v49
	v_cvt_pk_bf16_f32 v48, v42, v43
	v_lshl_add_u64 v[42:43], v[66:67], 0, s[8:9]
	v_cvt_pk_bf16_f32 v49, v44, v45
	global_store_dwordx4 v[42:43], v[46:49], off
	v_cvt_pk_bf16_f32 v38, v38, v39
	v_cvt_pk_bf16_f32 v39, v40, v41
	v_cvt_pk_bf16_f32 v40, v34, v35
	v_lshl_add_u64 v[34:35], v[66:67], 0, s[10:11]
	v_cvt_pk_bf16_f32 v41, v36, v37
	global_store_dwordx4 v[34:35], v[38:41], off
	v_cvt_pk_bf16_f32 v30, v30, v31
	v_cvt_pk_bf16_f32 v31, v32, v33
	v_cvt_pk_bf16_f32 v32, v26, v27
	v_lshl_add_u64 v[26:27], v[66:67], 0, s[12:13]
	v_cvt_pk_bf16_f32 v33, v28, v29
	global_store_dwordx4 v[26:27], v[30:33], off
	v_cvt_pk_bf16_f32 v22, v22, v23
	v_cvt_pk_bf16_f32 v23, v24, v25
	v_cvt_pk_bf16_f32 v24, v18, v19
	v_lshl_add_u64 v[18:19], v[66:67], 0, s[14:15]
	v_cvt_pk_bf16_f32 v25, v20, v21
	global_store_dwordx4 v[18:19], v[22:25], off
	v_cvt_pk_bf16_f32 v14, v14, v15
	v_cvt_pk_bf16_f32 v15, v16, v17
	v_cvt_pk_bf16_f32 v16, v10, v11
	v_lshl_add_u64 v[10:11], v[66:67], 0, s[16:17]
	v_cvt_pk_bf16_f32 v17, v12, v13
	global_store_dwordx4 v[10:11], v[14:17], off
	v_cvt_pk_bf16_f32 v6, v6, v7
	v_cvt_pk_bf16_f32 v7, v8, v9
	v_cvt_pk_bf16_f32 v8, v2, v3
	v_lshl_add_u64 v[2:3], v[66:67], 0, s[84:85]
	s_and_b64 vcc, exec, s[40:41]
	s_mov_b64 s[6:7], -1
	s_mov_b32 s79, 0x24000
	s_mov_b32 s84, 0x49000
	s_mov_b32 s85, 0x6d000
	v_cvt_pk_bf16_f32 v9, v4, v5
	global_store_dwordx4 v[2:3], v[6:9], off
	s_cbranch_vccnz .LBB0_168
	s_andn2_b64 vcc, exec, s[46:47]
	s_cbranch_vccnz .LBB0_167
	s_barrier
	s_branch .LBB0_167

.LBB0_340:
	s_add_i32 m0, s20, 0x18000
	v_lshl_add_u64 v[2:3], v[2:3], 0, s[34:35]
	s_waitcnt vmcnt(2)
	s_barrier
	global_load_lds_dwordx4 v[2:3], off
	v_lshl_add_u64 v[2:3], v[4:5], 0, s[34:35]
	s_add_i32 m0, s20, 0x1a000
	s_add_i32 s68, s20, 0x8000
	global_load_lds_dwordx4 v[2:3], off
	v_lshl_add_u64 v[2:3], v[10:11], 0, s[34:35]
	s_mov_b32 m0, s68
	s_add_i32 s70, s20, 0xa000
	global_load_lds_dwordx4 v[2:3], off
	v_lshl_add_u64 v[2:3], v[12:13], 0, s[34:35]
	s_mov_b32 m0, s70
	v_and_b32_e32 v20, 48, v0
	global_load_lds_dwordx4 v[2:3], off
	s_add_i32 m0, s20, 0x1c000
	v_lshl_add_u64 v[2:3], v[6:7], 0, s[34:35]
	global_load_lds_dwordx4 v[2:3], off
	v_lshl_add_u64 v[2:3], v[8:9], 0, s[34:35]
	s_add_i32 m0, s20, 0x1e000
	v_and_b32_e32 v21, 15, v0
	global_load_lds_dwordx4 v[2:3], off
	v_lshl_or_b32 v20, v21, 6, v20
	v_lshlrev_b32_e32 v21, 2, v0
	v_and_b32_e32 v143, 63, v0
	v_add_u32_e32 v0, v19, v17
	s_sext_i32_i8 s87, s6
	s_and_b32 s13, s13, 3
	s_lshr_b32 s63, s12, 6
	s_lshl_b32 s6, s5, 13
	v_and_b32_e32 v21, 32, v21
	v_add_lshl_u32 v0, v0, v18, 1
	v_bitop3_b32 v22, v20, s6, v21 bitop3:0xde
	s_lshl_b32 s6, s13, 12
	s_waitcnt vmcnt(6)
	s_add_i32 s72, s63, -2
	v_lshl_add_u64 v[138:139], s[38:39], 0, v[0:1]
	v_add_u32_e32 v0, v16, v14
	s_cmpk_lt_u32 s7, 0x100
	v_add_lshl_u32 v0, v0, v15, 1
	v_bitop3_b32 v142, v20, s6, v21 bitop3:0xde
	s_cselect_b64 s[6:7], -1, 0
	s_lshl_b32 s73, s13, 6
	s_lshl_b32 s78, s5, 7
	s_lshl_b32 s58, s14, 5
	s_mov_b32 s59, s39
	s_mov_b32 s5, s39
	s_mul_i32 s64, s14, 0xa0
	s_mov_b32 s65, s39
	v_lshl_add_u64 v[140:141], s[38:39], 0, v[0:1]
	s_mov_b32 s79, 0
	v_add_u32_e32 v144, 0, v22
	s_barrier
	s_mov_b32 s98, 0
	s_branch .LBB0_343

.LBB0_350:
	s_add_i32 s88, s10, 2
	s_add_u32 s89, s8, 0x80
	s_addc_u32 s11, s9, 0
	s_add_i32 s92, 0, 0x10000
	s_cmp_eq_u32 s72, s10
	s_cselect_b32 s11, s43, s11
	s_cselect_b32 s10, s42, s89
	v_add_u32_e32 v0, s92, v142
	s_cselect_b32 s91, s67, s13
	s_cselect_b32 s90, s66, s12
	s_add_i32 s89, 0, 0x14000
	ds_read_b128 v[146:149], v0
	ds_read_b128 v[150:153], v0 offset:1024
	ds_read_b128 v[154:157], v0 offset:2048
	ds_read_b128 v[158:161], v0 offset:3072
	v_add_u32_e32 v0, s89, v142
	ds_read_b128 v[166:169], v0
	ds_read_b128 v[170:173], v0 offset:1024
	ds_read_b128 v[174:177], v0 offset:2048
	ds_read_b128 v[178:181], v0 offset:3072
	v_lshl_add_u64 v[214:215], s[8:9], 0, v[138:139]
	s_add_i32 m0, s20, 0xc000
	ds_read_b128 v[182:185], v144
	ds_read_b128 v[186:189], v144 offset:1024
	ds_read_b128 v[190:193], v144 offset:2048
	ds_read_b128 v[194:197], v144 offset:3072
	ds_read_b128 v[198:201], v144 offset:4096
	ds_read_b128 v[202:205], v144 offset:5120
	ds_read_b128 v[206:209], v144 offset:6144
	ds_read_b128 v[210:213], v144 offset:7168
	global_load_lds_dwordx4 v[214:215], off
	v_lshl_add_u64 v[214:215], s[8:9], 0, v[140:141]
	s_add_i32 m0, s20, 0xe000
	s_nop 0
	global_load_lds_dwordx4 v[214:215], off
	s_cmp_lg_u32 s98, 0
	s_cbranch_scc1 .Lgw3a_r
	s_waitcnt vmcnt(8)
.Lgw3a_d:
	s_waitcnt lgkmcnt(0)
	s_barrier
	s_setprio 1
	s_waitcnt lgkmcnt(0)
	v_mfma_f32_16x16x32_bf16 v[126:129], v[146:149], v[182:185], v[126:129]
	v_mfma_f32_16x16x32_bf16 v[122:125], v[154:157], v[182:185], v[122:125]
	v_mfma_f32_16x16x32_bf16 v[118:121], v[146:149], v[190:193], v[118:121]
	v_mfma_f32_16x16x32_bf16 v[110:113], v[154:157], v[190:193], v[110:113]
	v_mfma_f32_16x16x32_bf16 v[102:105], v[146:149], v[198:201], v[102:105]
	v_mfma_f32_16x16x32_bf16 v[94:97], v[154:157], v[198:201], v[94:97]
	v_mfma_f32_16x16x32_bf16 v[86:89], v[146:149], v[206:209], v[86:89]
	v_mfma_f32_16x16x32_bf16 v[78:81], v[154:157], v[206:209], v[78:81]
	v_mfma_f32_16x16x32_bf16 v[126:129], v[150:153], v[186:189], v[126:129]
	v_mfma_f32_16x16x32_bf16 v[122:125], v[158:161], v[186:189], v[122:125]
	v_mfma_f32_16x16x32_bf16 v[118:121], v[150:153], v[194:197], v[118:121]
	v_mfma_f32_16x16x32_bf16 v[110:113], v[158:161], v[194:197], v[110:113]
	v_mfma_f32_16x16x32_bf16 v[102:105], v[150:153], v[202:205], v[102:105]
	v_mfma_f32_16x16x32_bf16 v[94:97], v[158:161], v[202:205], v[94:97]
	v_mfma_f32_16x16x32_bf16 v[86:89], v[150:153], v[210:213], v[86:89]
	v_mfma_f32_16x16x32_bf16 v[78:81], v[158:161], v[210:213], v[78:81]
	s_setprio 0
	s_setprio 1
	v_mfma_f32_16x16x32_bf16 v[114:117], v[166:169], v[182:185], v[114:117]
	v_mfma_f32_16x16x32_bf16 v[106:109], v[174:177], v[182:185], v[106:109]
	v_mfma_f32_16x16x32_bf16 v[98:101], v[166:169], v[190:193], v[98:101]
	v_mfma_f32_16x16x32_bf16 v[90:93], v[174:177], v[190:193], v[90:93]
	v_mfma_f32_16x16x32_bf16 v[82:85], v[166:169], v[198:201], v[82:85]
	v_mfma_f32_16x16x32_bf16 v[74:77], v[174:177], v[198:201], v[74:77]
	v_mfma_f32_16x16x32_bf16 v[70:73], v[166:169], v[206:209], v[70:73]
	v_mfma_f32_16x16x32_bf16 v[66:69], v[174:177], v[206:209], v[66:69]
	v_mfma_f32_16x16x32_bf16 v[114:117], v[170:173], v[186:189], v[114:117]
	v_mfma_f32_16x16x32_bf16 v[106:109], v[178:181], v[186:189], v[106:109]
	v_mfma_f32_16x16x32_bf16 v[98:101], v[170:173], v[194:197], v[98:101]
	v_mfma_f32_16x16x32_bf16 v[90:93], v[178:181], v[194:197], v[90:93]
	v_mfma_f32_16x16x32_bf16 v[82:85], v[170:173], v[202:205], v[82:85]
	v_mfma_f32_16x16x32_bf16 v[74:77], v[178:181], v[202:205], v[74:77]
	v_mfma_f32_16x16x32_bf16 v[70:73], v[170:173], v[210:213], v[70:73]
	v_mfma_f32_16x16x32_bf16 v[66:69], v[178:181], v[210:213], v[66:69]
	s_setprio 0
	s_barrier
	s_add_i32 s92, s92, s16
	v_lshl_add_u64 v[214:215], s[90:91], 0, v[134:135]
	s_mov_b32 m0, s92
	ds_read_b128 v[182:185], v144 offset:16384
	ds_read_b128 v[186:189], v144 offset:17408
	ds_read_b128 v[190:193], v144 offset:18432
	ds_read_b128 v[194:197], v144 offset:19456
	ds_read_b128 v[198:201], v144 offset:20480
	ds_read_b128 v[202:205], v144 offset:21504
	ds_read_b128 v[206:209], v144 offset:22528
	ds_read_b128 v[210:213], v144 offset:23552
	global_load_lds_dwordx4 v[214:215], off
	s_add_i32 m0, s92, 0x2000
	v_lshl_add_u64 v[216:217], s[90:91], 0, v[130:131]
	s_add_u32 s90, s90, s38
	s_addc_u32 s91, s91, 0
	s_add_i32 s89, s89, s16
	global_load_lds_dwordx4 v[216:217], off
	v_lshl_add_u64 v[218:219], s[90:91], 0, v[134:135]
	s_mov_b32 m0, s89
	v_lshl_add_u64 v[220:221], s[90:91], 0, v[130:131]
	global_load_lds_dwordx4 v[218:219], off
	s_add_i32 m0, s89, 0x2000
	v_lshl_add_u64 v[222:223], s[10:11], 0, v[136:137]
	global_load_lds_dwordx4 v[220:221], off
	s_mov_b32 m0, s20
	v_lshl_add_u64 v[236:237], s[10:11], 0, v[132:133]
	global_load_lds_dwordx4 v[222:223], off
	s_mov_b32 m0, s21
	s_nop 0
	global_load_lds_dwordx4 v[236:237], off
	s_cmp_lg_u32 s98, 0
	s_cbranch_scc1 .Lgw3b_r
	s_waitcnt vmcnt(8)
.Lgw3b_d:
	s_waitcnt lgkmcnt(0)
	s_barrier
	s_setprio 1
	s_waitcnt lgkmcnt(0)
	v_mfma_f32_16x16x32_bf16 v[62:65], v[146:149], v[182:185], v[62:65]
	v_mfma_f32_16x16x32_bf16 v[58:61], v[154:157], v[182:185], v[58:61]
	v_mfma_f32_16x16x32_bf16 v[54:57], v[146:149], v[190:193], v[54:57]
	v_mfma_f32_16x16x32_bf16 v[46:49], v[154:157], v[190:193], v[46:49]
	v_mfma_f32_16x16x32_bf16 v[38:41], v[146:149], v[198:201], v[38:41]
	v_mfma_f32_16x16x32_bf16 v[30:33], v[154:157], v[198:201], v[30:33]
	v_mfma_f32_16x16x32_bf16 v[22:25], v[146:149], v[206:209], v[22:25]
	v_mfma_f32_16x16x32_bf16 v[14:17], v[154:157], v[206:209], v[14:17]
	v_mfma_f32_16x16x32_bf16 v[62:65], v[150:153], v[186:189], v[62:65]
	v_mfma_f32_16x16x32_bf16 v[58:61], v[158:161], v[186:189], v[58:61]
	v_mfma_f32_16x16x32_bf16 v[54:57], v[150:153], v[194:197], v[54:57]
	v_mfma_f32_16x16x32_bf16 v[46:49], v[158:161], v[194:197], v[46:49]
	v_mfma_f32_16x16x32_bf16 v[38:41], v[150:153], v[202:205], v[38:41]
	v_mfma_f32_16x16x32_bf16 v[30:33], v[158:161], v[202:205], v[30:33]
	v_mfma_f32_16x16x32_bf16 v[22:25], v[150:153], v[210:213], v[22:25]
	v_mfma_f32_16x16x32_bf16 v[14:17], v[158:161], v[210:213], v[14:17]
	s_setprio 0
	s_setprio 1
	v_mfma_f32_16x16x32_bf16 v[50:53], v[166:169], v[182:185], v[50:53]
	v_mfma_f32_16x16x32_bf16 v[42:45], v[174:177], v[182:185], v[42:45]
	v_mfma_f32_16x16x32_bf16 v[34:37], v[166:169], v[190:193], v[34:37]
	v_mfma_f32_16x16x32_bf16 v[26:29], v[174:177], v[190:193], v[26:29]
	v_mfma_f32_16x16x32_bf16 v[18:21], v[166:169], v[198:201], v[18:21]
	v_mfma_f32_16x16x32_bf16 v[10:13], v[174:177], v[198:201], v[10:13]
	v_mfma_f32_16x16x32_bf16 v[6:9], v[166:169], v[206:209], v[6:9]
	v_mfma_f32_16x16x32_bf16 v[2:5], v[174:177], v[206:209], v[2:5]
	v_mfma_f32_16x16x32_bf16 v[50:53], v[170:173], v[186:189], v[50:53]
	v_mfma_f32_16x16x32_bf16 v[42:45], v[178:181], v[186:189], v[42:45]
	v_mfma_f32_16x16x32_bf16 v[34:37], v[170:173], v[194:197], v[34:37]
	v_mfma_f32_16x16x32_bf16 v[26:29], v[178:181], v[194:197], v[26:29]
	v_mfma_f32_16x16x32_bf16 v[18:21], v[170:173], v[202:205], v[18:21]
	v_mfma_f32_16x16x32_bf16 v[10:13], v[178:181], v[202:205], v[10:13]
	v_mfma_f32_16x16x32_bf16 v[6:9], v[170:173], v[210:213], v[6:9]
	v_mfma_f32_16x16x32_bf16 v[2:5], v[178:181], v[210:213], v[2:5]
	s_setprio 0
	s_barrier
	s_add_i32 s89, 0, 0x18000
	v_add_u32_e32 v0, s89, v142
	s_add_i32 s90, 0, 0x1c000
	ds_read_b128 v[146:149], v0
	ds_read_b128 v[150:153], v0 offset:1024
	ds_read_b128 v[154:157], v0 offset:2048
	ds_read_b128 v[158:161], v0 offset:3072
	v_add_u32_e32 v0, s90, v142
	ds_read_b128 v[166:169], v0
	ds_read_b128 v[170:173], v0 offset:1024
	ds_read_b128 v[174:177], v0 offset:2048
	ds_read_b128 v[178:181], v0 offset:3072
	s_add_u32 s10, s10, s38
	s_addc_u32 s11, s11, 0
	s_mov_b32 m0, s49
	v_lshl_add_u64 v[238:239], s[10:11], 0, v[136:137]
	ds_read_b128 v[182:185], v144 offset:32768
	ds_read_b128 v[186:189], v144 offset:33792
	ds_read_b128 v[190:193], v144 offset:34816
	ds_read_b128 v[194:197], v144 offset:35840
	ds_read_b128 v[198:201], v144 offset:36864
	ds_read_b128 v[202:205], v144 offset:37888
	ds_read_b128 v[206:209], v144 offset:38912
	ds_read_b128 v[210:213], v144 offset:39936
	global_load_lds_dwordx4 v[238:239], off
	v_lshl_add_u64 v[238:239], s[10:11], 0, v[132:133]
	s_mov_b32 m0, s62
	s_nop 0
	global_load_lds_dwordx4 v[238:239], off
	s_waitcnt vmcnt(8)
	s_waitcnt lgkmcnt(0)
	s_barrier
	s_setprio 1
	s_waitcnt lgkmcnt(0)
	v_mfma_f32_16x16x32_bf16 v[126:129], v[146:149], v[182:185], v[126:129]
	v_mfma_f32_16x16x32_bf16 v[122:125], v[154:157], v[182:185], v[122:125]
	v_mfma_f32_16x16x32_bf16 v[118:121], v[146:149], v[190:193], v[118:121]
	v_mfma_f32_16x16x32_bf16 v[110:113], v[154:157], v[190:193], v[110:113]
	v_mfma_f32_16x16x32_bf16 v[102:105], v[146:149], v[198:201], v[102:105]
	v_mfma_f32_16x16x32_bf16 v[94:97], v[154:157], v[198:201], v[94:97]
	v_mfma_f32_16x16x32_bf16 v[86:89], v[146:149], v[206:209], v[86:89]
	v_mfma_f32_16x16x32_bf16 v[78:81], v[154:157], v[206:209], v[78:81]
	v_mfma_f32_16x16x32_bf16 v[126:129], v[150:153], v[186:189], v[126:129]
	v_mfma_f32_16x16x32_bf16 v[122:125], v[158:161], v[186:189], v[122:125]
	v_mfma_f32_16x16x32_bf16 v[118:121], v[150:153], v[194:197], v[118:121]
	v_mfma_f32_16x16x32_bf16 v[110:113], v[158:161], v[194:197], v[110:113]
	v_mfma_f32_16x16x32_bf16 v[102:105], v[150:153], v[202:205], v[102:105]
	v_mfma_f32_16x16x32_bf16 v[94:97], v[158:161], v[202:205], v[94:97]
	v_mfma_f32_16x16x32_bf16 v[86:89], v[150:153], v[210:213], v[86:89]
	v_mfma_f32_16x16x32_bf16 v[78:81], v[158:161], v[210:213], v[78:81]
	s_setprio 0
	s_setprio 1
	v_mfma_f32_16x16x32_bf16 v[114:117], v[166:169], v[182:185], v[114:117]
	v_mfma_f32_16x16x32_bf16 v[106:109], v[174:177], v[182:185], v[106:109]
	v_mfma_f32_16x16x32_bf16 v[98:101], v[166:169], v[190:193], v[98:101]
	v_mfma_f32_16x16x32_bf16 v[90:93], v[174:177], v[190:193], v[90:93]
	v_mfma_f32_16x16x32_bf16 v[82:85], v[166:169], v[198:201], v[82:85]
	v_mfma_f32_16x16x32_bf16 v[74:77], v[174:177], v[198:201], v[74:77]
	v_mfma_f32_16x16x32_bf16 v[70:73], v[166:169], v[206:209], v[70:73]
	v_mfma_f32_16x16x32_bf16 v[66:69], v[174:177], v[206:209], v[66:69]
	v_mfma_f32_16x16x32_bf16 v[114:117], v[170:173], v[186:189], v[114:117]
	v_mfma_f32_16x16x32_bf16 v[106:109], v[178:181], v[186:189], v[106:109]
	v_mfma_f32_16x16x32_bf16 v[98:101], v[170:173], v[194:197], v[98:101]
	v_mfma_f32_16x16x32_bf16 v[90:93], v[178:181], v[194:197], v[90:93]
	v_mfma_f32_16x16x32_bf16 v[82:85], v[170:173], v[202:205], v[82:85]
	v_mfma_f32_16x16x32_bf16 v[74:77], v[178:181], v[202:205], v[74:77]
	v_mfma_f32_16x16x32_bf16 v[70:73], v[170:173], v[210:213], v[70:73]
	v_mfma_f32_16x16x32_bf16 v[66:69], v[178:181], v[210:213], v[66:69]
	s_setprio 0
	s_barrier
	s_add_i32 s10, s89, s16
	v_lshl_add_u64 v[214:215], v[214:215], 0, s[34:35]
	s_mov_b32 m0, s10
	ds_read_b128 v[182:185], v144 offset:49152
	ds_read_b128 v[186:189], v144 offset:50176
	ds_read_b128 v[190:193], v144 offset:51200
	ds_read_b128 v[194:197], v144 offset:52224
	ds_read_b128 v[198:201], v144 offset:53248
	ds_read_b128 v[202:205], v144 offset:54272
	ds_read_b128 v[206:209], v144 offset:55296
	ds_read_b128 v[210:213], v144 offset:56320
	global_load_lds_dwordx4 v[214:215], off
	v_lshl_add_u64 v[214:215], v[216:217], 0, s[34:35]
	s_add_i32 m0, s10, 0x2000
	s_add_i32 s10, s90, s16
	global_load_lds_dwordx4 v[214:215], off
	v_lshl_add_u64 v[214:215], v[218:219], 0, s[34:35]
	s_mov_b32 m0, s10
	s_nop 0
	global_load_lds_dwordx4 v[214:215], off
	v_lshl_add_u64 v[214:215], v[220:221], 0, s[34:35]
	s_add_i32 m0, s10, 0x2000
	s_nop 0
	global_load_lds_dwordx4 v[214:215], off
	v_lshl_add_u64 v[214:215], v[222:223], 0, s[34:35]
	s_mov_b32 m0, s68
	s_nop 0
	global_load_lds_dwordx4 v[214:215], off
	v_lshl_add_u64 v[214:215], v[236:237], 0, s[34:35]
	s_mov_b32 m0, s70
	s_nop 0
	global_load_lds_dwordx4 v[214:215], off
	s_waitcnt vmcnt(8)
	s_waitcnt lgkmcnt(0)
	s_barrier
	s_setprio 1
	s_waitcnt lgkmcnt(0)
	v_mfma_f32_16x16x32_bf16 v[62:65], v[146:149], v[182:185], v[62:65]
	v_mfma_f32_16x16x32_bf16 v[58:61], v[154:157], v[182:185], v[58:61]
	v_mfma_f32_16x16x32_bf16 v[54:57], v[146:149], v[190:193], v[54:57]
	v_mfma_f32_16x16x32_bf16 v[46:49], v[154:157], v[190:193], v[46:49]
	v_mfma_f32_16x16x32_bf16 v[38:41], v[146:149], v[198:201], v[38:41]
	v_mfma_f32_16x16x32_bf16 v[30:33], v[154:157], v[198:201], v[30:33]
	v_mfma_f32_16x16x32_bf16 v[22:25], v[146:149], v[206:209], v[22:25]
	v_mfma_f32_16x16x32_bf16 v[14:17], v[154:157], v[206:209], v[14:17]
	v_mfma_f32_16x16x32_bf16 v[62:65], v[150:153], v[186:189], v[62:65]
	v_mfma_f32_16x16x32_bf16 v[58:61], v[158:161], v[186:189], v[58:61]
	v_mfma_f32_16x16x32_bf16 v[54:57], v[150:153], v[194:197], v[54:57]
	v_mfma_f32_16x16x32_bf16 v[46:49], v[158:161], v[194:197], v[46:49]
	v_mfma_f32_16x16x32_bf16 v[38:41], v[150:153], v[202:205], v[38:41]
	v_mfma_f32_16x16x32_bf16 v[30:33], v[158:161], v[202:205], v[30:33]
	v_mfma_f32_16x16x32_bf16 v[22:25], v[150:153], v[210:213], v[22:25]
	v_mfma_f32_16x16x32_bf16 v[14:17], v[158:161], v[210:213], v[14:17]
	s_setprio 0
	s_setprio 1
	v_mfma_f32_16x16x32_bf16 v[50:53], v[166:169], v[182:185], v[50:53]
	v_mfma_f32_16x16x32_bf16 v[42:45], v[174:177], v[182:185], v[42:45]
	v_mfma_f32_16x16x32_bf16 v[34:37], v[166:169], v[190:193], v[34:37]
	v_mfma_f32_16x16x32_bf16 v[26:29], v[174:177], v[190:193], v[26:29]
	v_mfma_f32_16x16x32_bf16 v[18:21], v[166:169], v[198:201], v[18:21]
	v_mfma_f32_16x16x32_bf16 v[10:13], v[174:177], v[198:201], v[10:13]
	v_mfma_f32_16x16x32_bf16 v[6:9], v[166:169], v[206:209], v[6:9]
	v_mfma_f32_16x16x32_bf16 v[2:5], v[174:177], v[206:209], v[2:5]
	v_mfma_f32_16x16x32_bf16 v[50:53], v[170:173], v[186:189], v[50:53]
	v_mfma_f32_16x16x32_bf16 v[42:45], v[178:181], v[186:189], v[42:45]
	v_mfma_f32_16x16x32_bf16 v[34:37], v[170:173], v[194:197], v[34:37]
	v_mfma_f32_16x16x32_bf16 v[26:29], v[178:181], v[194:197], v[26:29]
	v_mfma_f32_16x16x32_bf16 v[18:21], v[170:173], v[202:205], v[18:21]
	v_mfma_f32_16x16x32_bf16 v[10:13], v[178:181], v[202:205], v[10:13]
	v_mfma_f32_16x16x32_bf16 v[6:9], v[170:173], v[210:213], v[6:9]
	v_mfma_f32_16x16x32_bf16 v[2:5], v[178:181], v[210:213], v[2:5]
	s_setprio 0
	s_barrier
	s_add_u32 s8, s8, 0x100
	s_addc_u32 s9, s9, 0
	s_add_u32 s12, s12, 0x100
	s_addc_u32 s13, s13, 0
	s_cmp_ge_u32 s88, s63
	s_mov_b32 s10, s88
	s_cbranch_scc0 .LBB0_350
	s_and_b64 vcc, exec, s[6:7]
	s_cbranch_vccz .LBB0_353
	s_barrier
.LBB0_353:
	s_mov_b32 s98, 1
	s_lshl_b32 s8, s84, 8
	s_mul_hi_i32 s9, s8, s14
	s_mul_i32 s8, s8, s14
	s_lshl_b64 s[8:9], s[8:9], 1
	s_add_u32 s10, s46, s8
	v_mov_b32_e32 v0, v143
	s_addc_u32 s11, s47, s9
	s_lshl_b32 s8, s87, 8
	s_ashr_i32 s9, s8, 31
	v_lshlrev_b32_e32 v145, 1, v0
	s_lshl_b64 s[8:9], s[8:9], 1
	v_and_or_b32 v145, v145, 30, s78
	s_add_u32 s8, s10, s8
	v_mul_lo_u32 v145, v145, s14
	v_and_b32_e32 v0, -16, v0
	s_addc_u32 s9, s11, s9
	v_add3_u32 v0, v0, s73, v145
	v_lshl_add_u64 v[146:147], s[8:9], 0, v[0:1]
	v_cvt_pk_bf16_f32 v126, v126, v127
	v_cvt_pk_bf16_f32 v127, v128, v129
	v_cvt_pk_bf16_f32 v128, v122, v123
	v_cvt_pk_bf16_f32 v129, v124, v125
	global_store_dwordx4 v0, v[126:129], s[8:9]
	v_cvt_pk_bf16_f32 v114, v114, v115
	v_cvt_pk_bf16_f32 v115, v116, v117
	v_cvt_pk_bf16_f32 v116, v106, v107
	v_cvt_pk_bf16_f32 v117, v108, v109
	global_store_dwordx4 v0, v[114:117], s[8:9] offset:256
	v_cvt_pk_bf16_f32 v106, v118, v119
	v_cvt_pk_bf16_f32 v107, v120, v121
	v_cvt_pk_bf16_f32 v108, v110, v111
	v_lshl_add_u64 v[110:111], v[146:147], 0, s[58:59]
	v_cvt_pk_bf16_f32 v109, v112, v113
	global_store_dwordx4 v[110:111], v[106:109], off
	v_cvt_pk_bf16_f32 v98, v98, v99
	v_cvt_pk_bf16_f32 v99, v100, v101
	v_cvt_pk_bf16_f32 v100, v90, v91
	v_cvt_pk_bf16_f32 v101, v92, v93
	global_store_dwordx4 v[110:111], v[98:101], off offset:256
	v_cvt_pk_bf16_f32 v90, v102, v103
	v_cvt_pk_bf16_f32 v91, v104, v105
	v_cvt_pk_bf16_f32 v92, v94, v95
	v_lshl_add_u64 v[94:95], v[110:111], 0, s[58:59]
	v_cvt_pk_bf16_f32 v93, v96, v97
	global_store_dwordx4 v[94:95], v[90:93], off
	v_cvt_pk_bf16_f32 v82, v82, v83
	v_cvt_pk_bf16_f32 v83, v84, v85
	v_cvt_pk_bf16_f32 v84, v74, v75
	v_cvt_pk_bf16_f32 v85, v76, v77
	global_store_dwordx4 v[94:95], v[82:85], off offset:256
	v_cvt_pk_bf16_f32 v74, v86, v87
	v_cvt_pk_bf16_f32 v75, v88, v89
	v_cvt_pk_bf16_f32 v76, v78, v79
	v_lshl_add_u64 v[78:79], v[94:95], 0, s[58:59]
	v_cvt_pk_bf16_f32 v77, v80, v81
	global_store_dwordx4 v[78:79], v[74:77], off
	v_cvt_pk_bf16_f32 v70, v70, v71
	v_cvt_pk_bf16_f32 v71, v72, v73
	v_cvt_pk_bf16_f32 v72, v66, v67
	v_cvt_pk_bf16_f32 v73, v68, v69
	global_store_dwordx4 v[78:79], v[70:73], off offset:256
	v_cvt_pk_bf16_f32 v62, v62, v63
	v_cvt_pk_bf16_f32 v63, v64, v65
	v_cvt_pk_bf16_f32 v64, v58, v59
	v_lshl_add_u64 v[58:59], v[78:79], 0, s[64:65]
	v_cvt_pk_bf16_f32 v65, v60, v61
	global_store_dwordx4 v[58:59], v[62:65], off
	v_cvt_pk_bf16_f32 v50, v50, v51
	v_cvt_pk_bf16_f32 v51, v52, v53
	v_cvt_pk_bf16_f32 v52, v42, v43
	v_cvt_pk_bf16_f32 v53, v44, v45
	global_store_dwordx4 v[58:59], v[50:53], off offset:256
	v_cvt_pk_bf16_f32 v42, v54, v55
	v_cvt_pk_bf16_f32 v43, v56, v57
	v_cvt_pk_bf16_f32 v44, v46, v47
	v_lshl_add_u64 v[46:47], v[58:59], 0, s[58:59]
	v_cvt_pk_bf16_f32 v45, v48, v49
	global_store_dwordx4 v[46:47], v[42:45], off
	v_cvt_pk_bf16_f32 v34, v34, v35
	v_cvt_pk_bf16_f32 v35, v36, v37
	v_cvt_pk_bf16_f32 v36, v26, v27
	v_cvt_pk_bf16_f32 v37, v28, v29
	global_store_dwordx4 v[46:47], v[34:37], off offset:256
	v_cvt_pk_bf16_f32 v26, v38, v39
	v_cvt_pk_bf16_f32 v27, v40, v41
	v_cvt_pk_bf16_f32 v28, v30, v31
	v_lshl_add_u64 v[30:31], v[46:47], 0, s[58:59]
	v_cvt_pk_bf16_f32 v29, v32, v33
	global_store_dwordx4 v[30:31], v[26:29], off
	v_cvt_pk_bf16_f32 v18, v18, v19
	v_cvt_pk_bf16_f32 v19, v20, v21
	v_cvt_pk_bf16_f32 v20, v10, v11
	v_cvt_pk_bf16_f32 v21, v12, v13
	global_store_dwordx4 v[30:31], v[18:21], off offset:256
	v_cvt_pk_bf16_f32 v10, v22, v23
	v_cvt_pk_bf16_f32 v11, v24, v25
	v_cvt_pk_bf16_f32 v12, v14, v15
	v_lshl_add_u64 v[14:15], v[30:31], 0, s[58:59]
	s_and_b64 vcc, exec, s[40:41]
	s_mov_b64 s[8:9], -1
	v_cvt_pk_bf16_f32 v13, v16, v17
	global_store_dwordx4 v[14:15], v[10:13], off
	v_cvt_pk_bf16_f32 v6, v6, v7
	v_cvt_pk_bf16_f32 v7, v8, v9
	v_cvt_pk_bf16_f32 v8, v2, v3
	v_cvt_pk_bf16_f32 v9, v4, v5
	global_store_dwordx4 v[14:15], v[6:9], off offset:256
	s_cbranch_vccnz .LBB0_342
	s_andn2_b64 vcc, exec, s[56:57]
	s_cbranch_vccnz .LBB0_341
	s_barrier
	s_branch .LBB0_341

	.amdhsa_kernel _Z8mega_fwd4Args
		.amdhsa_group_segment_fixed_size 0
		.amdhsa_private_segment_fixed_size 0
		.amdhsa_kernarg_size 512
		.amdhsa_user_sgpr_count 2
		.amdhsa_user_sgpr_dispatch_ptr 0
		.amdhsa_user_sgpr_queue_ptr 0
		.amdhsa_user_sgpr_kernarg_segment_ptr 1
		.amdhsa_user_sgpr_dispatch_id 0
		.amdhsa_user_sgpr_kernarg_preload_length 0
		.amdhsa_user_sgpr_kernarg_preload_offset 0
		.amdhsa_user_sgpr_private_segment_size 0
		.amdhsa_uses_dynamic_stack 0
		.amdhsa_enable_private_segment 0
		.amdhsa_system_sgpr_workgroup_id_x 1
		.amdhsa_system_sgpr_workgroup_id_y 0
		.amdhsa_system_sgpr_workgroup_id_z 0
		.amdhsa_system_sgpr_workgroup_info 0
		.amdhsa_system_vgpr_workitem_id 2
		.amdhsa_next_free_vgpr 255
		.amdhsa_next_free_sgpr 99
		.amdhsa_accum_offset 256
		.amdhsa_reserve_vcc 1
		.amdhsa_float_round_mode_32 0
		.amdhsa_float_round_mode_16_64 0
		.amdhsa_float_denorm_mode_32 3
		.amdhsa_float_denorm_mode_16_64 3
		.amdhsa_dx10_clamp 1
		.amdhsa_ieee_mode 1
		.amdhsa_fp16_overflow 0
		.amdhsa_tg_split 0
		.amdhsa_exception_fp_ieee_invalid_op 0
		.amdhsa_exception_fp_denorm_src 0
		.amdhsa_exception_fp_ieee_div_zero 0
		.amdhsa_exception_fp_ieee_overflow 0
		.amdhsa_exception_fp_ieee_underflow 0
		.amdhsa_exception_fp_ieee_inexact 0
		.amdhsa_exception_int_div_zero 0
	.end_amdhsa_kernel

.Lfunc_end0:
	.size	_Z8mega_fwd4Args, .Lfunc_end0-_Z8mega_fwd4Args
	.set _Z8mega_fwd4Args.num_vgpr, 255
	.set _Z8mega_fwd4Args.num_agpr, 0
	.set _Z8mega_fwd4Args.numbered_sgpr, 99
	.set _Z8mega_fwd4Args.num_named_barrier, 0
	.set _Z8mega_fwd4Args.private_seg_size, 0
	.set _Z8mega_fwd4Args.uses_vcc, 1
	.set _Z8mega_fwd4Args.uses_flat_scratch, 0
	.set _Z8mega_fwd4Args.has_dyn_sized_stack, 0
	.set _Z8mega_fwd4Args.has_recursion, 0
	.set _Z8mega_fwd4Args.has_indirect_call, 0

amdhsa.kernels:
  - .agpr_count:     0
    .args:
      - .offset:         0
        .size:           256
        .value_kind:     by_value
      - .offset:         256
        .size:           4
        .value_kind:     hidden_block_count_x
      - .offset:         260
        .size:           4
        .value_kind:     hidden_block_count_y
      - .offset:         264
        .size:           4
        .value_kind:     hidden_block_count_z
      - .offset:         268
        .size:           2
        .value_kind:     hidden_group_size_x
      - .offset:         270
        .size:           2
        .value_kind:     hidden_group_size_y
      - .offset:         272
        .size:           2
        .value_kind:     hidden_group_size_z
      - .offset:         274
        .size:           2
        .value_kind:     hidden_remainder_x
      - .offset:         276
        .size:           2
        .value_kind:     hidden_remainder_y
      - .offset:         278
        .size:           2
        .value_kind:     hidden_remainder_z
      - .offset:         296
        .size:           8
        .value_kind:     hidden_global_offset_x
      - .offset:         304
        .size:           8
        .value_kind:     hidden_global_offset_y
      - .offset:         312
        .size:           8
        .value_kind:     hidden_global_offset_z
      - .offset:         320
        .size:           2
        .value_kind:     hidden_grid_dims
      - .offset:         344
        .size:           8
        .value_kind:     hidden_multigrid_sync_arg
      - .offset:         376
        .size:           4
        .value_kind:     hidden_dynamic_lds_size
    .group_segment_fixed_size: 0
    .kernarg_segment_align: 8
    .kernarg_segment_size: 512
    .language:       OpenCL C
    .language_version:
      - 2
      - 0
    .max_flat_workgroup_size: 512
    .name:           _Z8mega_fwd4Args
    .private_segment_fixed_size: 0
    .sgpr_count:     105
    .sgpr_spill_count: 149
    .symbol:         _Z8mega_fwd4Args.kd
    .uniform_work_group_size: 1
    .uses_dynamic_stack: false
    .vgpr_count:     255
    .vgpr_spill_count: 0
    .wavefront_size: 64
